# GEMM main loops (P2,P4,P6,P7): per-cluster s_setprio flips removed, one static s_setprio 1 for the younger wave half (waves 4-7) per tile, reset after the loop
# speedup vs baseline: 1.0142x; 1.0017x over previous
; template <class Epi>
; __device__ __forceinline__ void gemm_phase(LAS unsigned char* lds, const Gemm g, const StaticOrder& S, const Epi& E) {
;     ...
;     for (;;) {
;         const bool has_next = S.next(ui + 1, npm, npn, nk0, nnk, nsp);
;         const char* nA = has_next ? (const char*)g.A + (size_t)npm * tstep + (size_t)nk0 * kstep : cA; const char* nB = has_next ? (const char*)g.Bt + (size_t)npn * tstep + (size_t)nk0 * kstep : cB;
;         const int nt = cnk;
;         for (int t = 0; t < nt; t += 2) {
.LBB0_564:
	s_cmpk_gt_u32 s5, 0xff
	s_cbranch_scc0 .Lmy_prio_p2
	s_setprio 1

; #define PG8_STAGE(bufoff, gbase, voff) do { _Pragma("unroll") for (int _i = 0; _i < 2; ++_i) \
;         __builtin_amdgcn_global_load_lds((const unsigned*)((const char*)(gbase) + (voff)[_i]), (LAS unsigned*)(lds + (bufoff) + ldsw + _i * 8192), 16, 0, 0); } while (0)
; #define PG8_LDA(dst, b, h) do { _Pragma("unroll") for (int m = 0; m < 4; ++m) _Pragma("unroll") for (int k = 0; k < 2; ++k) dst[m][k] = *(const LAS bf16x8*)(lds + PG8_SA(b, h) + aoff + m * 2048 + k * 1024); } while (0)
; #define PG8_LDB(dst, b, h) do { _Pragma("unroll") for (int n = 0; n < 2; ++n) _Pragma("unroll") for (int k = 0; k < 2; ++k) dst[n][k] = *(const LAS bf16x8*)(lds + PG8_SB(b, h) + boff + n * 2048 + k * 1024); } while (0)
; #define PG8_MMA(ai, bj, At, Bt) do { __builtin_amdgcn_s_setprio(1); _Pragma("unroll") for (int m = 0; m < 4; ++m) _Pragma("unroll") for (int n = 0; n < 2; ++n) _Pragma("unroll") for (int k = 0; k < 2; ++k) \
;         acc[ai][bj][m][n] = __builtin_amdgcn_mfma_f32_16x16x32_bf16(Bt[n][k], At[m][k], acc[ai][bj][m][n], 0, 0, 0); __builtin_amdgcn_s_setprio(0); } while (0)
; #define PG8_WAIT_L(n) asm volatile("s_waitcnt lgkmcnt(" #n ")" ::: "memory")
; #define PG8_BAR __builtin_amdgcn_s_barrier()
; #define PG8_SCHED __builtin_amdgcn_sched_barrier(0)
; template <class Epi>
; __device__ __forceinline__ void gemm_phase(LAS unsigned char* lds, const Gemm g, const StaticOrder& S, const Epi& E) {
;     ...
;             PG8_LDB(B0, 0, 0); PG8_SCHED; PG8_LDA(At, 0, 0); PG8_STAGE(PG8_SA(1, 1), a1 + hstep, voffA);
;             PG8_WAIT_L(8); PG8_BAR; PG8_WAIT_L(0); PG8_MMA(0, 0, At, B0); PG8_BAR; PG8_SCHED;
;             PG8_LDB(B1, 0, 1); PG8_STAGE(PG8_SB(0, 0), b2, voffB);
;             PG8_BAR; PG8_WAIT_L(0); PG8_MMA(0, 1, At, B1); PG8_BAR;
;             PG8_LDA(At, 0, 1); PG8_STAGE(PG8_SA(0, 0), a2, voffA);
;             PG8_BAR; PG8_WAIT_L(0); PG8_MMA(1, 0, At, B0); PG8_BAR; PG8_SCHED;
.LBB0_568:
	s_add_i32 s74, s52, 2
	s_add_u32 s30, s50, 0xfffc0080
	s_addc_u32 s31, s51, -1
	s_add_i32 s75, 0, 0x10000
	v_add_u32_e32 v158, s75, v163
	ds_read_b128 v[136:139], v158
	ds_read_b128 v[150:153], v158 offset:1024
	ds_read_b128 v[154:157], v158 offset:2048
	ds_read_b128 v[158:161], v158 offset:3072
	s_cmp_eq_u32 s63, s52
	s_cselect_b32 s52, s61, s72
	s_cselect_b32 s71, s33, s31
	s_cselect_b32 s70, s38, s30
	s_cselect_b32 s53, s39, s73
	v_lshl_add_u64 v[182:183], s[50:51], 0, v[148:149]
	s_add_i32 m0, s18, 0xc000
	ds_read_b128 v[166:169], v165
	ds_read_b128 v[170:173], v165 offset:1024
	ds_read_b128 v[174:177], v165 offset:2048
	ds_read_b128 v[178:181], v165 offset:3072
	ds_read_b128 v[186:189], v165 offset:4096
	ds_read_b128 v[190:193], v165 offset:5120
	ds_read_b128 v[194:197], v165 offset:6144
	ds_read_b128 v[198:201], v165 offset:7168
	global_load_lds_dwordx4 v[182:183], off
	v_lshl_add_u64 v[182:183], s[50:51], 0, v[146:147]
	s_add_i32 m0, s18, 0xe000
	s_nop 0
	global_load_lds_dwordx4 v[182:183], off
	s_waitcnt lgkmcnt(8)
	s_barrier
	s_waitcnt lgkmcnt(0)
	s_waitcnt lgkmcnt(0)
	v_mfma_f32_16x16x32_bf16 v[132:135], v[136:139], v[166:169], v[132:135]
	v_mfma_f32_16x16x32_bf16 v[128:131], v[154:157], v[166:169], v[128:131]
	v_mfma_f32_16x16x32_bf16 v[116:119], v[136:139], v[174:177], v[116:119]
	v_mfma_f32_16x16x32_bf16 v[112:115], v[154:157], v[174:177], v[112:115]
	v_mfma_f32_16x16x32_bf16 v[100:103], v[136:139], v[186:189], v[100:103]
	v_mfma_f32_16x16x32_bf16 v[96:99], v[154:157], v[186:189], v[96:99]
	v_mfma_f32_16x16x32_bf16 v[84:87], v[136:139], v[194:197], v[84:87]
	v_mfma_f32_16x16x32_bf16 v[80:83], v[154:157], v[194:197], v[80:83]
	v_mfma_f32_16x16x32_bf16 v[132:135], v[150:153], v[170:173], v[132:135]
	v_mfma_f32_16x16x32_bf16 v[128:131], v[158:161], v[170:173], v[128:131]
	v_mfma_f32_16x16x32_bf16 v[116:119], v[150:153], v[178:181], v[116:119]
	v_mfma_f32_16x16x32_bf16 v[112:115], v[158:161], v[178:181], v[112:115]
	v_mfma_f32_16x16x32_bf16 v[100:103], v[150:153], v[190:193], v[100:103]
	v_mfma_f32_16x16x32_bf16 v[96:99], v[158:161], v[190:193], v[96:99]
	v_mfma_f32_16x16x32_bf16 v[84:87], v[150:153], v[198:201], v[84:87]
	v_mfma_f32_16x16x32_bf16 v[80:83], v[158:161], v[198:201], v[80:83]
	s_barrier
	s_add_i32 s76, 0, 0x14000
	v_add_u32_e32 v182, s76, v163
	s_add_i32 s30, s75, s6
	ds_read_b128 v[232:235], v182
	ds_read_b128 v[236:239], v182 offset:1024
	ds_read_b128 v[240:243], v182 offset:2048
	ds_read_b128 v[244:247], v182 offset:3072
	v_lshl_add_u64 v[182:183], s[52:53], 0, v[0:1]
	s_mov_b32 m0, s30
	v_lshl_add_u64 v[248:249], s[52:53], 0, v[2:3]
	global_load_lds_dwordx4 v[182:183], off
	s_add_i32 m0, s30, 0x2000
	s_nop 0
	global_load_lds_dwordx4 v[248:249], off
	s_barrier
	s_waitcnt lgkmcnt(0)
	s_waitcnt lgkmcnt(0)
	v_mfma_f32_16x16x32_bf16 v[124:127], v[232:235], v[166:169], v[124:127]
	v_mfma_f32_16x16x32_bf16 v[120:123], v[240:243], v[166:169], v[120:123]
	v_mfma_f32_16x16x32_bf16 v[108:111], v[232:235], v[174:177], v[108:111]
	v_mfma_f32_16x16x32_bf16 v[104:107], v[240:243], v[174:177], v[104:107]
	v_mfma_f32_16x16x32_bf16 v[92:95], v[232:235], v[186:189], v[92:95]
	v_mfma_f32_16x16x32_bf16 v[88:91], v[240:243], v[186:189], v[88:91]
	v_mfma_f32_16x16x32_bf16 v[76:79], v[232:235], v[194:197], v[76:79]
	v_mfma_f32_16x16x32_bf16 v[72:75], v[240:243], v[194:197], v[72:75]
	v_mfma_f32_16x16x32_bf16 v[124:127], v[236:239], v[170:173], v[124:127]
	v_mfma_f32_16x16x32_bf16 v[120:123], v[244:247], v[170:173], v[120:123]
	v_mfma_f32_16x16x32_bf16 v[108:111], v[236:239], v[178:181], v[108:111]
	v_mfma_f32_16x16x32_bf16 v[104:107], v[244:247], v[178:181], v[104:107]
	v_mfma_f32_16x16x32_bf16 v[92:95], v[236:239], v[190:193], v[92:95]
	v_mfma_f32_16x16x32_bf16 v[88:91], v[244:247], v[190:193], v[88:91]
	v_mfma_f32_16x16x32_bf16 v[76:79], v[236:239], v[198:201], v[76:79]
	v_mfma_f32_16x16x32_bf16 v[72:75], v[244:247], v[198:201], v[72:75]
	s_mov_b32 m0, s18
	v_lshl_add_u64 v[250:251], s[70:71], 0, v[142:143]
	s_barrier
	ds_read_b128 v[166:169], v165 offset:16384
	ds_read_b128 v[170:173], v165 offset:17408
	ds_read_b128 v[174:177], v165 offset:18432
	ds_read_b128 v[178:181], v165 offset:19456
	ds_read_b128 v[186:189], v165 offset:20480
	ds_read_b128 v[190:193], v165 offset:21504
	ds_read_b128 v[194:197], v165 offset:22528
	ds_read_b128 v[198:201], v165 offset:23552
	global_load_lds_dwordx4 v[250:251], off
	v_lshl_add_u64 v[218:219], s[70:71], 0, v[140:141]
	s_mov_b32 m0, s19
	s_nop 0
	global_load_lds_dwordx4 v[218:219], off
	s_barrier
	s_waitcnt lgkmcnt(0)
	s_waitcnt lgkmcnt(0)
	v_mfma_f32_16x16x32_bf16 v[68:71], v[136:139], v[166:169], v[68:71]
	v_mfma_f32_16x16x32_bf16 v[64:67], v[154:157], v[166:169], v[64:67]
	v_mfma_f32_16x16x32_bf16 v[52:55], v[136:139], v[174:177], v[52:55]
	v_mfma_f32_16x16x32_bf16 v[48:51], v[154:157], v[174:177], v[48:51]
	v_mfma_f32_16x16x32_bf16 v[36:39], v[136:139], v[186:189], v[36:39]
	v_mfma_f32_16x16x32_bf16 v[32:35], v[154:157], v[186:189], v[32:35]
	v_mfma_f32_16x16x32_bf16 v[20:23], v[136:139], v[194:197], v[20:23]
	v_mfma_f32_16x16x32_bf16 v[16:19], v[154:157], v[194:197], v[16:19]
	v_mfma_f32_16x16x32_bf16 v[68:71], v[150:153], v[170:173], v[68:71]
	v_mfma_f32_16x16x32_bf16 v[64:67], v[158:161], v[170:173], v[64:67]
	v_mfma_f32_16x16x32_bf16 v[52:55], v[150:153], v[178:181], v[52:55]
	v_mfma_f32_16x16x32_bf16 v[48:51], v[158:161], v[178:181], v[48:51]
	v_mfma_f32_16x16x32_bf16 v[36:39], v[150:153], v[190:193], v[36:39]
	v_mfma_f32_16x16x32_bf16 v[32:35], v[158:161], v[190:193], v[32:35]
	v_mfma_f32_16x16x32_bf16 v[20:23], v[150:153], v[198:201], v[20:23]
	v_mfma_f32_16x16x32_bf16 v[16:19], v[158:161], v[198:201], v[16:19]
	s_barrier
; #define PG8_STAGE(bufoff, gbase, voff) do { _Pragma("unroll") for (int _i = 0; _i < 2; ++_i) \
;         __builtin_amdgcn_global_load_lds((const unsigned*)((const char*)(gbase) + (voff)[_i]), (LAS unsigned*)(lds + (bufoff) + ldsw + _i * 8192), 16, 0, 0); } while (0)
; #define PG8_LDA(dst, b, h) do { _Pragma("unroll") for (int m = 0; m < 4; ++m) _Pragma("unroll") for (int k = 0; k < 2; ++k) dst[m][k] = *(const LAS bf16x8*)(lds + PG8_SA(b, h) + aoff + m * 2048 + k * 1024); } while (0)
; #define PG8_LDB(dst, b, h) do { _Pragma("unroll") for (int n = 0; n < 2; ++n) _Pragma("unroll") for (int k = 0; k < 2; ++k) dst[n][k] = *(const LAS bf16x8*)(lds + PG8_SB(b, h) + boff + n * 2048 + k * 1024); } while (0)
; #define PG8_MMA(ai, bj, At, Bt) do { __builtin_amdgcn_s_setprio(1); _Pragma("unroll") for (int m = 0; m < 4; ++m) _Pragma("unroll") for (int n = 0; n < 2; ++n) _Pragma("unroll") for (int k = 0; k < 2; ++k) \
;         acc[ai][bj][m][n] = __builtin_amdgcn_mfma_f32_16x16x32_bf16(Bt[n][k], At[m][k], acc[ai][bj][m][n], 0, 0, 0); __builtin_amdgcn_s_setprio(0); } while (0)
; #define PG8_WAIT_V(n) asm volatile("s_waitcnt vmcnt(" #n ")" ::: "memory")
; #define PG8_WAIT_L(n) asm volatile("s_waitcnt lgkmcnt(" #n ")" ::: "memory")
; #define PG8_BAR __builtin_amdgcn_s_barrier()
; #define PG8_SCHED __builtin_amdgcn_sched_barrier(0)
; template <class Epi>
; __device__ __forceinline__ void gemm_phase(LAS unsigned char* lds, const Gemm g, const StaticOrder& S, const Epi& E) {
;     ...
;             PG8_STAGE(PG8_SB(0, 1), b2 + hstep, voffB);
;             PG8_WAIT_V(6); PG8_BAR; PG8_MMA(1, 1, At, B1); PG8_BAR;
;             PG8_LDB(B0, 1, 0); PG8_SCHED; PG8_LDA(At, 1, 0); PG8_STAGE(PG8_SA(0, 1), a2 + hstep, voffA);
;             PG8_WAIT_L(8); PG8_BAR; PG8_WAIT_L(0); PG8_MMA(0, 0, At, B0); PG8_BAR; PG8_SCHED;
;             PG8_LDB(B1, 1, 1); PG8_STAGE(PG8_SB(1, 0), b3, voffB);
	s_add_u32 s30, s52, 0x40000
	s_addc_u32 s31, s53, 0
	s_add_i32 s75, s76, s6
	v_lshl_add_u64 v[136:137], s[30:31], 0, v[0:1]
	s_mov_b32 m0, s75
	s_nop 0
	global_load_lds_dwordx4 v[136:137], off
	v_lshl_add_u64 v[136:137], s[30:31], 0, v[2:3]
	s_add_i32 m0, s75, 0x2000
	s_nop 0
	global_load_lds_dwordx4 v[136:137], off
	s_waitcnt vmcnt(6)
	s_barrier
	v_mfma_f32_16x16x32_bf16 v[60:63], v[232:235], v[166:169], v[60:63]
	v_mfma_f32_16x16x32_bf16 v[56:59], v[240:243], v[166:169], v[56:59]
	v_mfma_f32_16x16x32_bf16 v[44:47], v[232:235], v[174:177], v[44:47]
	v_mfma_f32_16x16x32_bf16 v[40:43], v[240:243], v[174:177], v[40:43]
	v_mfma_f32_16x16x32_bf16 v[28:31], v[232:235], v[186:189], v[28:31]
	v_mfma_f32_16x16x32_bf16 v[24:27], v[240:243], v[186:189], v[24:27]
	v_mfma_f32_16x16x32_bf16 v[12:15], v[232:235], v[194:197], v[12:15]
	v_mfma_f32_16x16x32_bf16 v[8:11], v[240:243], v[194:197], v[8:11]
	v_mfma_f32_16x16x32_bf16 v[60:63], v[236:239], v[170:173], v[60:63]
	v_mfma_f32_16x16x32_bf16 v[56:59], v[244:247], v[170:173], v[56:59]
	v_mfma_f32_16x16x32_bf16 v[44:47], v[236:239], v[178:181], v[44:47]
	v_mfma_f32_16x16x32_bf16 v[40:43], v[244:247], v[178:181], v[40:43]
	v_mfma_f32_16x16x32_bf16 v[28:31], v[236:239], v[190:193], v[28:31]
	v_mfma_f32_16x16x32_bf16 v[24:27], v[244:247], v[190:193], v[24:27]
	v_mfma_f32_16x16x32_bf16 v[12:15], v[236:239], v[198:201], v[12:15]
	v_mfma_f32_16x16x32_bf16 v[8:11], v[244:247], v[198:201], v[8:11]
	s_add_i32 s75, 0, 0x18000
	v_add_u32_e32 v158, s75, v163
	s_barrier
	ds_read_b128 v[136:139], v158
	ds_read_b128 v[150:153], v158 offset:1024
	ds_read_b128 v[154:157], v158 offset:2048
	ds_read_b128 v[158:161], v158 offset:3072
	s_add_u32 s30, s70, 0x40000
	s_addc_u32 s31, s71, 0
	s_mov_b32 m0, s20
	v_lshl_add_u64 v[232:233], s[30:31], 0, v[142:143]
	ds_read_b128 v[166:169], v165 offset:32768
	ds_read_b128 v[170:173], v165 offset:33792
	ds_read_b128 v[174:177], v165 offset:34816
	ds_read_b128 v[178:181], v165 offset:35840
	ds_read_b128 v[186:189], v165 offset:36864
	ds_read_b128 v[190:193], v165 offset:37888
	ds_read_b128 v[194:197], v165 offset:38912
	ds_read_b128 v[198:201], v165 offset:39936
	global_load_lds_dwordx4 v[232:233], off
	v_lshl_add_u64 v[232:233], s[30:31], 0, v[140:141]
	s_mov_b32 m0, s21
	s_nop 0
	global_load_lds_dwordx4 v[232:233], off
	s_waitcnt lgkmcnt(8)
	s_barrier
	s_waitcnt lgkmcnt(0)
	s_waitcnt lgkmcnt(0)
	v_mfma_f32_16x16x32_bf16 v[132:135], v[136:139], v[166:169], v[132:135]
	v_mfma_f32_16x16x32_bf16 v[128:131], v[154:157], v[166:169], v[128:131]
	v_mfma_f32_16x16x32_bf16 v[116:119], v[136:139], v[174:177], v[116:119]
	v_mfma_f32_16x16x32_bf16 v[112:115], v[154:157], v[174:177], v[112:115]
	v_mfma_f32_16x16x32_bf16 v[100:103], v[136:139], v[186:189], v[100:103]
	v_mfma_f32_16x16x32_bf16 v[96:99], v[154:157], v[186:189], v[96:99]
	v_mfma_f32_16x16x32_bf16 v[84:87], v[136:139], v[194:197], v[84:87]
	v_mfma_f32_16x16x32_bf16 v[80:83], v[154:157], v[194:197], v[80:83]
	v_mfma_f32_16x16x32_bf16 v[132:135], v[150:153], v[170:173], v[132:135]
	v_mfma_f32_16x16x32_bf16 v[128:131], v[158:161], v[170:173], v[128:131]
	v_mfma_f32_16x16x32_bf16 v[116:119], v[150:153], v[178:181], v[116:119]
	v_mfma_f32_16x16x32_bf16 v[112:115], v[158:161], v[178:181], v[112:115]
	v_mfma_f32_16x16x32_bf16 v[100:103], v[150:153], v[190:193], v[100:103]
	v_mfma_f32_16x16x32_bf16 v[96:99], v[158:161], v[190:193], v[96:99]
	v_mfma_f32_16x16x32_bf16 v[84:87], v[150:153], v[198:201], v[84:87]
	v_mfma_f32_16x16x32_bf16 v[80:83], v[158:161], v[198:201], v[80:83]
	s_barrier
	s_add_i32 s70, 0, 0x1c000
	s_add_i32 s30, s75, s6
	v_add_u32_e32 v185, s70, v163
	v_lshl_add_u64 v[182:183], v[182:183], 0, s[12:13]
	s_mov_b32 m0, s30
	ds_read_b128 v[232:235], v185
	ds_read_b128 v[236:239], v185 offset:1024
	ds_read_b128 v[240:243], v185 offset:2048
	ds_read_b128 v[244:247], v185 offset:3072
	global_load_lds_dwordx4 v[182:183], off
	v_lshl_add_u64 v[182:183], v[248:249], 0, s[12:13]
	s_add_i32 m0, s30, 0x2000
	s_nop 0
	global_load_lds_dwordx4 v[182:183], off
	s_barrier
; #define PG8_STAGE(bufoff, gbase, voff) do { _Pragma("unroll") for (int _i = 0; _i < 2; ++_i) \
;         __builtin_amdgcn_global_load_lds((const unsigned*)((const char*)(gbase) + (voff)[_i]), (LAS unsigned*)(lds + (bufoff) + ldsw + _i * 8192), 16, 0, 0); } while (0)
; #define PG8_LDA(dst, b, h) do { _Pragma("unroll") for (int m = 0; m < 4; ++m) _Pragma("unroll") for (int k = 0; k < 2; ++k) dst[m][k] = *(const LAS bf16x8*)(lds + PG8_SA(b, h) + aoff + m * 2048 + k * 1024); } while (0)
; #define PG8_LDB(dst, b, h) do { _Pragma("unroll") for (int n = 0; n < 2; ++n) _Pragma("unroll") for (int k = 0; k < 2; ++k) dst[n][k] = *(const LAS bf16x8*)(lds + PG8_SB(b, h) + boff + n * 2048 + k * 1024); } while (0)
; #define PG8_MMA(ai, bj, At, Bt) do { __builtin_amdgcn_s_setprio(1); _Pragma("unroll") for (int m = 0; m < 4; ++m) _Pragma("unroll") for (int n = 0; n < 2; ++n) _Pragma("unroll") for (int k = 0; k < 2; ++k) \
;         acc[ai][bj][m][n] = __builtin_amdgcn_mfma_f32_16x16x32_bf16(Bt[n][k], At[m][k], acc[ai][bj][m][n], 0, 0, 0); __builtin_amdgcn_s_setprio(0); } while (0)
; #define PG8_WAIT_V(n) asm volatile("s_waitcnt vmcnt(" #n ")" ::: "memory")
; #define PG8_WAIT_L(n) asm volatile("s_waitcnt lgkmcnt(" #n ")" ::: "memory")
; #define PG8_BAR __builtin_amdgcn_s_barrier()
; #define PG8_SCHED __builtin_amdgcn_sched_barrier(0)
; template <class Epi>
; __device__ __forceinline__ void gemm_phase(LAS unsigned char* lds, const Gemm g, const StaticOrder& S, const Epi& E) {
;     ...
;             PG8_WAIT_L(8); PG8_BAR; PG8_WAIT_L(0); PG8_MMA(0, 0, At, B0); PG8_BAR; PG8_SCHED;
;             PG8_LDB(B1, 1, 1); PG8_STAGE(PG8_SB(1, 0), b3, voffB);
;             PG8_BAR; PG8_WAIT_L(0); PG8_MMA(0, 1, At, B1); PG8_BAR;
;             PG8_LDA(At, 1, 1); PG8_STAGE(PG8_SA(1, 0), a3, voffA);
;             PG8_BAR; PG8_WAIT_L(0); PG8_MMA(1, 0, At, B0); PG8_BAR; PG8_SCHED;
;             PG8_STAGE(PG8_SB(1, 1), b3 + hstep, voffB);
;             PG8_WAIT_V(6); PG8_BAR; PG8_MMA(1, 1, At, B1); PG8_BAR;
;         }
	s_waitcnt lgkmcnt(0)
	s_waitcnt lgkmcnt(0)
	v_mfma_f32_16x16x32_bf16 v[124:127], v[232:235], v[166:169], v[124:127]
	v_mfma_f32_16x16x32_bf16 v[120:123], v[240:243], v[166:169], v[120:123]
	v_mfma_f32_16x16x32_bf16 v[108:111], v[232:235], v[174:177], v[108:111]
	v_mfma_f32_16x16x32_bf16 v[104:107], v[240:243], v[174:177], v[104:107]
	v_mfma_f32_16x16x32_bf16 v[92:95], v[232:235], v[186:189], v[92:95]
	v_mfma_f32_16x16x32_bf16 v[88:91], v[240:243], v[186:189], v[88:91]
	v_mfma_f32_16x16x32_bf16 v[76:79], v[232:235], v[194:197], v[76:79]
	v_mfma_f32_16x16x32_bf16 v[72:75], v[240:243], v[194:197], v[72:75]
	v_mfma_f32_16x16x32_bf16 v[124:127], v[236:239], v[170:173], v[124:127]
	v_mfma_f32_16x16x32_bf16 v[120:123], v[244:247], v[170:173], v[120:123]
	v_mfma_f32_16x16x32_bf16 v[108:111], v[236:239], v[178:181], v[108:111]
	v_mfma_f32_16x16x32_bf16 v[104:107], v[244:247], v[178:181], v[104:107]
	v_mfma_f32_16x16x32_bf16 v[92:95], v[236:239], v[190:193], v[92:95]
	v_mfma_f32_16x16x32_bf16 v[88:91], v[244:247], v[190:193], v[88:91]
	v_mfma_f32_16x16x32_bf16 v[76:79], v[236:239], v[198:201], v[76:79]
	v_mfma_f32_16x16x32_bf16 v[72:75], v[244:247], v[198:201], v[72:75]
	s_mov_b32 m0, s22
	v_lshl_add_u64 v[182:183], v[250:251], 0, s[12:13]
	s_barrier
	ds_read_b128 v[166:169], v165 offset:49152
	ds_read_b128 v[170:173], v165 offset:50176
	ds_read_b128 v[174:177], v165 offset:51200
	ds_read_b128 v[178:181], v165 offset:52224
	ds_read_b128 v[186:189], v165 offset:53248
	ds_read_b128 v[190:193], v165 offset:54272
	ds_read_b128 v[194:197], v165 offset:55296
	ds_read_b128 v[198:201], v165 offset:56320
	global_load_lds_dwordx4 v[182:183], off
	v_lshl_add_u64 v[182:183], v[218:219], 0, s[12:13]
	s_mov_b32 m0, s23
	s_nop 0
	global_load_lds_dwordx4 v[182:183], off
	s_barrier
	s_waitcnt lgkmcnt(0)
	s_waitcnt lgkmcnt(0)
	v_mfma_f32_16x16x32_bf16 v[68:71], v[136:139], v[166:169], v[68:71]
	v_mfma_f32_16x16x32_bf16 v[64:67], v[154:157], v[166:169], v[64:67]
	v_mfma_f32_16x16x32_bf16 v[52:55], v[136:139], v[174:177], v[52:55]
	v_mfma_f32_16x16x32_bf16 v[48:51], v[154:157], v[174:177], v[48:51]
	v_mfma_f32_16x16x32_bf16 v[36:39], v[136:139], v[186:189], v[36:39]
	v_mfma_f32_16x16x32_bf16 v[32:35], v[154:157], v[186:189], v[32:35]
	v_mfma_f32_16x16x32_bf16 v[20:23], v[136:139], v[194:197], v[20:23]
	v_mfma_f32_16x16x32_bf16 v[16:19], v[154:157], v[194:197], v[16:19]
	v_mfma_f32_16x16x32_bf16 v[68:71], v[150:153], v[170:173], v[68:71]
	v_mfma_f32_16x16x32_bf16 v[64:67], v[158:161], v[170:173], v[64:67]
	v_mfma_f32_16x16x32_bf16 v[52:55], v[150:153], v[178:181], v[52:55]
	v_mfma_f32_16x16x32_bf16 v[48:51], v[158:161], v[178:181], v[48:51]
	v_mfma_f32_16x16x32_bf16 v[36:39], v[150:153], v[190:193], v[36:39]
	v_mfma_f32_16x16x32_bf16 v[32:35], v[158:161], v[190:193], v[32:35]
	v_mfma_f32_16x16x32_bf16 v[20:23], v[150:153], v[198:201], v[20:23]
	v_mfma_f32_16x16x32_bf16 v[16:19], v[158:161], v[198:201], v[16:19]
	s_barrier
	s_add_u32 s30, s52, 0x40080
	s_addc_u32 s31, s53, 0
	s_add_i32 s52, s70, s6
	v_lshl_add_u64 v[136:137], s[30:31], 0, v[0:1]
	s_mov_b32 m0, s52
	s_nop 0
	global_load_lds_dwordx4 v[136:137], off
	v_lshl_add_u64 v[136:137], s[30:31], 0, v[2:3]
	s_add_i32 m0, s52, 0x2000
	s_nop 0
	global_load_lds_dwordx4 v[136:137], off
	s_waitcnt vmcnt(6)
	s_barrier
	v_mfma_f32_16x16x32_bf16 v[60:63], v[232:235], v[166:169], v[60:63]
	v_mfma_f32_16x16x32_bf16 v[56:59], v[240:243], v[166:169], v[56:59]
	v_mfma_f32_16x16x32_bf16 v[44:47], v[232:235], v[174:177], v[44:47]
	v_mfma_f32_16x16x32_bf16 v[40:43], v[240:243], v[174:177], v[40:43]
	v_mfma_f32_16x16x32_bf16 v[28:31], v[232:235], v[186:189], v[28:31]
	v_mfma_f32_16x16x32_bf16 v[24:27], v[240:243], v[186:189], v[24:27]
	v_mfma_f32_16x16x32_bf16 v[12:15], v[232:235], v[194:197], v[12:15]
	v_mfma_f32_16x16x32_bf16 v[8:11], v[240:243], v[194:197], v[8:11]
	v_mfma_f32_16x16x32_bf16 v[60:63], v[236:239], v[170:173], v[60:63]
	v_mfma_f32_16x16x32_bf16 v[56:59], v[244:247], v[170:173], v[56:59]
	v_mfma_f32_16x16x32_bf16 v[44:47], v[236:239], v[178:181], v[44:47]
	v_mfma_f32_16x16x32_bf16 v[40:43], v[244:247], v[178:181], v[40:43]
	v_mfma_f32_16x16x32_bf16 v[28:31], v[236:239], v[190:193], v[28:31]
	v_mfma_f32_16x16x32_bf16 v[24:27], v[244:247], v[190:193], v[24:27]
	v_mfma_f32_16x16x32_bf16 v[12:15], v[236:239], v[198:201], v[12:15]
	v_mfma_f32_16x16x32_bf16 v[8:11], v[244:247], v[198:201], v[8:11]
	s_add_u32 s72, s72, 0x100
	s_addc_u32 s73, s73, 0
	s_add_u32 s50, s50, 0x100
	s_addc_u32 s51, s51, 0
	s_cmp_ge_u32 s74, s29
	s_mov_b32 s52, s74
	s_barrier
	s_cbranch_scc0 .LBB0_568
	s_branch .LBB0_570

; #define PG8_WAIT_V(n) asm volatile("s_waitcnt vmcnt(" #n ")" ::: "memory")
; #define PG8_BAR __builtin_amdgcn_s_barrier()
; template <class Epi>
; __device__ __forceinline__ void gemm_phase(LAS unsigned char* lds, const Gemm g, const StaticOrder& S, const Epi& E) {
;     ...
;     PG8_WAIT_V(0);
;     if (wr == 0) PG8_BAR;
;     PG8_BAR;
.LBB0_713:
	s_setprio 0
	s_waitcnt vmcnt(0)
	s_cmpk_gt_u32 s5, 0xff
	s_cbranch_scc1 .LBB0_715
	s_barrier

; template <class Epi>
; __device__ __forceinline__ void gemm_phase(LAS unsigned char* lds, const Gemm g, const StaticOrder& S, const Epi& E) {
;     ...
;     for (;;) {
;         const bool has_next = S.next(ui + 1, npm, npn, nk0, nnk, nsp);
;         const char* nA = has_next ? (const char*)g.A + (size_t)npm * tstep + (size_t)nk0 * kstep : cA; const char* nB = has_next ? (const char*)g.Bt + (size_t)npn * tstep + (size_t)nk0 * kstep : cB;
;         const int nt = cnk;
;         for (int t = 0; t < nt; t += 2) {
.LBB0_1482:
	s_cmpk_gt_u32 s3, 0xff
	s_cbranch_scc0 .Lmy_prio_p4
	s_setprio 1

; #define PG8_STAGE(bufoff, gbase, voff) do { _Pragma("unroll") for (int _i = 0; _i < 2; ++_i) \
;         __builtin_amdgcn_global_load_lds((const unsigned*)((const char*)(gbase) + (voff)[_i]), (LAS unsigned*)(lds + (bufoff) + ldsw + _i * 8192), 16, 0, 0); } while (0)
; #define PG8_LDA(dst, b, h) do { _Pragma("unroll") for (int m = 0; m < 4; ++m) _Pragma("unroll") for (int k = 0; k < 2; ++k) dst[m][k] = *(const LAS bf16x8*)(lds + PG8_SA(b, h) + aoff + m * 2048 + k * 1024); } while (0)
; #define PG8_LDB(dst, b, h) do { _Pragma("unroll") for (int n = 0; n < 2; ++n) _Pragma("unroll") for (int k = 0; k < 2; ++k) dst[n][k] = *(const LAS bf16x8*)(lds + PG8_SB(b, h) + boff + n * 2048 + k * 1024); } while (0)
; #define PG8_MMA(ai, bj, At, Bt) do { __builtin_amdgcn_s_setprio(1); _Pragma("unroll") for (int m = 0; m < 4; ++m) _Pragma("unroll") for (int n = 0; n < 2; ++n) _Pragma("unroll") for (int k = 0; k < 2; ++k) \
;         acc[ai][bj][m][n] = __builtin_amdgcn_mfma_f32_16x16x32_bf16(Bt[n][k], At[m][k], acc[ai][bj][m][n], 0, 0, 0); __builtin_amdgcn_s_setprio(0); } while (0)
; #define PG8_WAIT_L(n) asm volatile("s_waitcnt lgkmcnt(" #n ")" ::: "memory")
; #define PG8_BAR __builtin_amdgcn_s_barrier()
; #define PG8_SCHED __builtin_amdgcn_sched_barrier(0)
; template <class Epi>
; __device__ __forceinline__ void gemm_phase(LAS unsigned char* lds, const Gemm g, const StaticOrder& S, const Epi& E) {
;     ...
;             PG8_LDB(B0, 0, 0); PG8_SCHED; PG8_LDA(At, 0, 0); PG8_STAGE(PG8_SA(1, 1), a1 + hstep, voffA);
;             PG8_WAIT_L(8); PG8_BAR; PG8_WAIT_L(0); PG8_MMA(0, 0, At, B0); PG8_BAR; PG8_SCHED;
;             PG8_LDB(B1, 0, 1); PG8_STAGE(PG8_SB(0, 0), b2, voffB);
;             PG8_BAR; PG8_WAIT_L(0); PG8_MMA(0, 1, At, B1); PG8_BAR;
;             PG8_LDA(At, 0, 1); PG8_STAGE(PG8_SA(0, 0), a2, voffA);
;             PG8_BAR; PG8_WAIT_L(0); PG8_MMA(1, 0, At, B0); PG8_BAR; PG8_SCHED;
.LBB0_1489:
	s_add_i32 s30, s94, 2
	s_add_u32 s74, s72, 0x100
	s_addc_u32 s75, s73, 0
	s_add_i32 s31, 0, 0x10000
	v_add_u32_e32 v148, s31, v231
	ds_read_b128 v[136:139], v148
	ds_read_b128 v[140:143], v148 offset:1024
	ds_read_b128 v[144:147], v148 offset:2048
	ds_read_b128 v[148:151], v148 offset:3072
	s_cmp_eq_u32 s91, s94
	s_cselect_b32 s94, s69, s96
	s_cselect_b32 vcc_hi, s49, s75
	s_cselect_b32 vcc_lo, s61, s74
	s_cselect_b32 s95, s67, s97
	v_lshl_add_u64 v[190:191], s[72:73], 0, v[188:189]
	s_add_i32 m0, s78, 0xc000
	ds_read_b128 v[152:155], v233
	ds_read_b128 v[156:159], v233 offset:1024
	ds_read_b128 v[160:163], v233 offset:2048
	ds_read_b128 v[164:167], v233 offset:3072
	ds_read_b128 v[168:171], v233 offset:4096
	ds_read_b128 v[172:175], v233 offset:5120
	ds_read_b128 v[176:179], v233 offset:6144
	ds_read_b128 v[180:183], v233 offset:7168
	global_load_lds_dwordx4 v[190:191], off
	v_lshl_add_u64 v[190:191], s[72:73], 0, v[186:187]
	s_add_i32 m0, s78, 0xe000
	s_nop 0
	global_load_lds_dwordx4 v[190:191], off
	s_waitcnt lgkmcnt(8)
	s_barrier
	s_waitcnt lgkmcnt(0)
	s_waitcnt lgkmcnt(0)
	v_mfma_f32_16x16x32_bf16 v[132:135], v[136:139], v[152:155], v[132:135]
	v_mfma_f32_16x16x32_bf16 v[128:131], v[144:147], v[152:155], v[128:131]
	v_mfma_f32_16x16x32_bf16 v[116:119], v[136:139], v[160:163], v[116:119]
	v_mfma_f32_16x16x32_bf16 v[112:115], v[144:147], v[160:163], v[112:115]
	v_mfma_f32_16x16x32_bf16 v[100:103], v[136:139], v[168:171], v[100:103]
	v_mfma_f32_16x16x32_bf16 v[96:99], v[144:147], v[168:171], v[96:99]
	v_mfma_f32_16x16x32_bf16 v[84:87], v[136:139], v[176:179], v[84:87]
	v_mfma_f32_16x16x32_bf16 v[80:83], v[144:147], v[176:179], v[80:83]
	v_mfma_f32_16x16x32_bf16 v[132:135], v[140:143], v[156:159], v[132:135]
	v_mfma_f32_16x16x32_bf16 v[128:131], v[148:151], v[156:159], v[128:131]
	v_mfma_f32_16x16x32_bf16 v[116:119], v[140:143], v[164:167], v[116:119]
	v_mfma_f32_16x16x32_bf16 v[112:115], v[148:151], v[164:167], v[112:115]
	v_mfma_f32_16x16x32_bf16 v[100:103], v[140:143], v[172:175], v[100:103]
	v_mfma_f32_16x16x32_bf16 v[96:99], v[148:151], v[172:175], v[96:99]
	v_mfma_f32_16x16x32_bf16 v[84:87], v[140:143], v[180:183], v[84:87]
	v_mfma_f32_16x16x32_bf16 v[80:83], v[148:151], v[180:183], v[80:83]
	s_barrier
	s_add_i32 s8, 0, 0x14000
	v_add_u32_e32 v218, s8, v231
	s_add_i32 s31, s31, s33
	ds_read_b128 v[190:193], v218
	ds_read_b128 v[194:197], v218 offset:1024
	ds_read_b128 v[198:201], v218 offset:2048
	ds_read_b128 v[234:237], v218 offset:3072
	v_lshl_add_u64 v[218:219], s[94:95], 0, v[0:1]
	s_mov_b32 m0, s31
	v_lshl_add_u64 v[238:239], s[94:95], 0, v[2:3]
	global_load_lds_dwordx4 v[218:219], off
	s_add_i32 m0, s31, 0x2000
	s_nop 0
	global_load_lds_dwordx4 v[238:239], off
	s_barrier
	s_waitcnt lgkmcnt(0)
	s_waitcnt lgkmcnt(0)
	v_mfma_f32_16x16x32_bf16 v[124:127], v[190:193], v[152:155], v[124:127]
	v_mfma_f32_16x16x32_bf16 v[120:123], v[198:201], v[152:155], v[120:123]
	v_mfma_f32_16x16x32_bf16 v[108:111], v[190:193], v[160:163], v[108:111]
	v_mfma_f32_16x16x32_bf16 v[104:107], v[198:201], v[160:163], v[104:107]
	v_mfma_f32_16x16x32_bf16 v[92:95], v[190:193], v[168:171], v[92:95]
	v_mfma_f32_16x16x32_bf16 v[88:91], v[198:201], v[168:171], v[88:91]
	v_mfma_f32_16x16x32_bf16 v[76:79], v[190:193], v[176:179], v[76:79]
	v_mfma_f32_16x16x32_bf16 v[72:75], v[198:201], v[176:179], v[72:75]
	v_mfma_f32_16x16x32_bf16 v[124:127], v[194:197], v[156:159], v[124:127]
	v_mfma_f32_16x16x32_bf16 v[120:123], v[234:237], v[156:159], v[120:123]
	v_mfma_f32_16x16x32_bf16 v[108:111], v[194:197], v[164:167], v[108:111]
	v_mfma_f32_16x16x32_bf16 v[104:107], v[234:237], v[164:167], v[104:107]
	v_mfma_f32_16x16x32_bf16 v[92:95], v[194:197], v[172:175], v[92:95]
	v_mfma_f32_16x16x32_bf16 v[88:91], v[234:237], v[172:175], v[88:91]
	v_mfma_f32_16x16x32_bf16 v[76:79], v[194:197], v[180:183], v[76:79]
	v_mfma_f32_16x16x32_bf16 v[72:75], v[234:237], v[180:183], v[72:75]
	s_mov_b32 m0, s78
	v_lshl_add_u64 v[240:241], vcc, 0, v[0:1]
	s_barrier
	ds_read_b128 v[152:155], v233 offset:16384
	ds_read_b128 v[156:159], v233 offset:17408
	ds_read_b128 v[160:163], v233 offset:18432
	ds_read_b128 v[164:167], v233 offset:19456
	ds_read_b128 v[168:171], v233 offset:20480
	ds_read_b128 v[172:175], v233 offset:21504
	ds_read_b128 v[176:179], v233 offset:22528
	ds_read_b128 v[180:183], v233 offset:23552
	global_load_lds_dwordx4 v[240:241], off
	v_lshl_add_u64 v[242:243], vcc, 0, v[2:3]
	s_mov_b32 m0, s18
	s_nop 0
	global_load_lds_dwordx4 v[242:243], off
	s_barrier
	s_waitcnt lgkmcnt(0)
	s_waitcnt lgkmcnt(0)
	v_mfma_f32_16x16x32_bf16 v[68:71], v[136:139], v[152:155], v[68:71]
	v_mfma_f32_16x16x32_bf16 v[64:67], v[144:147], v[152:155], v[64:67]
	v_mfma_f32_16x16x32_bf16 v[52:55], v[136:139], v[160:163], v[52:55]
	v_mfma_f32_16x16x32_bf16 v[48:51], v[144:147], v[160:163], v[48:51]
	v_mfma_f32_16x16x32_bf16 v[36:39], v[136:139], v[168:171], v[36:39]
	v_mfma_f32_16x16x32_bf16 v[32:35], v[144:147], v[168:171], v[32:35]
	v_mfma_f32_16x16x32_bf16 v[20:23], v[136:139], v[176:179], v[20:23]
	v_mfma_f32_16x16x32_bf16 v[16:19], v[144:147], v[176:179], v[16:19]
	v_mfma_f32_16x16x32_bf16 v[68:71], v[140:143], v[156:159], v[68:71]
	v_mfma_f32_16x16x32_bf16 v[64:67], v[148:151], v[156:159], v[64:67]
	v_mfma_f32_16x16x32_bf16 v[52:55], v[140:143], v[164:167], v[52:55]
	v_mfma_f32_16x16x32_bf16 v[48:51], v[148:151], v[164:167], v[48:51]
	v_mfma_f32_16x16x32_bf16 v[36:39], v[140:143], v[172:175], v[36:39]
	v_mfma_f32_16x16x32_bf16 v[32:35], v[148:151], v[172:175], v[32:35]
	v_mfma_f32_16x16x32_bf16 v[20:23], v[140:143], v[180:183], v[20:23]
	v_mfma_f32_16x16x32_bf16 v[16:19], v[148:151], v[180:183], v[16:19]
	s_barrier
; #define PG8_STAGE(bufoff, gbase, voff) do { _Pragma("unroll") for (int _i = 0; _i < 2; ++_i) \
;         __builtin_amdgcn_global_load_lds((const unsigned*)((const char*)(gbase) + (voff)[_i]), (LAS unsigned*)(lds + (bufoff) + ldsw + _i * 8192), 16, 0, 0); } while (0)
; #define PG8_LDA(dst, b, h) do { _Pragma("unroll") for (int m = 0; m < 4; ++m) _Pragma("unroll") for (int k = 0; k < 2; ++k) dst[m][k] = *(const LAS bf16x8*)(lds + PG8_SA(b, h) + aoff + m * 2048 + k * 1024); } while (0)
; #define PG8_LDB(dst, b, h) do { _Pragma("unroll") for (int n = 0; n < 2; ++n) _Pragma("unroll") for (int k = 0; k < 2; ++k) dst[n][k] = *(const LAS bf16x8*)(lds + PG8_SB(b, h) + boff + n * 2048 + k * 1024); } while (0)
; #define PG8_MMA(ai, bj, At, Bt) do { __builtin_amdgcn_s_setprio(1); _Pragma("unroll") for (int m = 0; m < 4; ++m) _Pragma("unroll") for (int n = 0; n < 2; ++n) _Pragma("unroll") for (int k = 0; k < 2; ++k) \
;         acc[ai][bj][m][n] = __builtin_amdgcn_mfma_f32_16x16x32_bf16(Bt[n][k], At[m][k], acc[ai][bj][m][n], 0, 0, 0); __builtin_amdgcn_s_setprio(0); } while (0)
; #define PG8_WAIT_V(n) asm volatile("s_waitcnt vmcnt(" #n ")" ::: "memory")
; #define PG8_WAIT_L(n) asm volatile("s_waitcnt lgkmcnt(" #n ")" ::: "memory")
; #define PG8_BAR __builtin_amdgcn_s_barrier()
; #define PG8_SCHED __builtin_amdgcn_sched_barrier(0)
; template <class Epi>
; __device__ __forceinline__ void gemm_phase(LAS unsigned char* lds, const Gemm g, const StaticOrder& S, const Epi& E) {
;     ...
;             PG8_STAGE(PG8_SB(0, 1), b2 + hstep, voffB);
;             PG8_WAIT_V(6); PG8_BAR; PG8_MMA(1, 1, At, B1); PG8_BAR;
;             PG8_LDB(B0, 1, 0); PG8_SCHED; PG8_LDA(At, 1, 0); PG8_STAGE(PG8_SA(0, 1), a2 + hstep, voffA);
;             PG8_WAIT_L(8); PG8_BAR; PG8_WAIT_L(0); PG8_MMA(0, 0, At, B0); PG8_BAR; PG8_SCHED;
;             PG8_LDB(B1, 1, 1); PG8_STAGE(PG8_SB(1, 0), b3, voffB);
	s_add_u32 s72, s94, 0x40000
	s_addc_u32 s73, s95, 0
	s_add_i32 s8, s8, s33
	v_lshl_add_u64 v[136:137], s[72:73], 0, v[0:1]
	s_mov_b32 m0, s8
	s_nop 0
	global_load_lds_dwordx4 v[136:137], off
	v_lshl_add_u64 v[136:137], s[72:73], 0, v[2:3]
	s_add_i32 m0, s8, 0x2000
	s_nop 0
	global_load_lds_dwordx4 v[136:137], off
	s_waitcnt vmcnt(6)
	s_barrier
	v_mfma_f32_16x16x32_bf16 v[60:63], v[190:193], v[152:155], v[60:63]
	v_mfma_f32_16x16x32_bf16 v[56:59], v[198:201], v[152:155], v[56:59]
	v_mfma_f32_16x16x32_bf16 v[44:47], v[190:193], v[160:163], v[44:47]
	v_mfma_f32_16x16x32_bf16 v[40:43], v[198:201], v[160:163], v[40:43]
	v_mfma_f32_16x16x32_bf16 v[28:31], v[190:193], v[168:171], v[28:31]
	v_mfma_f32_16x16x32_bf16 v[24:27], v[198:201], v[168:171], v[24:27]
	v_mfma_f32_16x16x32_bf16 v[12:15], v[190:193], v[176:179], v[12:15]
	v_mfma_f32_16x16x32_bf16 v[8:11], v[198:201], v[176:179], v[8:11]
	v_mfma_f32_16x16x32_bf16 v[60:63], v[194:197], v[156:159], v[60:63]
	v_mfma_f32_16x16x32_bf16 v[56:59], v[234:237], v[156:159], v[56:59]
	v_mfma_f32_16x16x32_bf16 v[44:47], v[194:197], v[164:167], v[44:47]
	v_mfma_f32_16x16x32_bf16 v[40:43], v[234:237], v[164:167], v[40:43]
	v_mfma_f32_16x16x32_bf16 v[28:31], v[194:197], v[172:175], v[28:31]
	v_mfma_f32_16x16x32_bf16 v[24:27], v[234:237], v[172:175], v[24:27]
	v_mfma_f32_16x16x32_bf16 v[12:15], v[194:197], v[180:183], v[12:15]
	v_mfma_f32_16x16x32_bf16 v[8:11], v[234:237], v[180:183], v[8:11]
	s_add_i32 s8, 0, 0x18000
	v_add_u32_e32 v148, s8, v231
	s_barrier
	ds_read_b128 v[136:139], v148
	ds_read_b128 v[140:143], v148 offset:1024
	ds_read_b128 v[144:147], v148 offset:2048
	ds_read_b128 v[148:151], v148 offset:3072
	s_add_u32 s72, vcc_lo, 0x40000
	s_addc_u32 s73, vcc_hi, 0
	s_mov_b32 m0, s19
	v_lshl_add_u64 v[190:191], s[72:73], 0, v[0:1]
	ds_read_b128 v[152:155], v233 offset:32768
	ds_read_b128 v[156:159], v233 offset:33792
	ds_read_b128 v[160:163], v233 offset:34816
	ds_read_b128 v[164:167], v233 offset:35840
	ds_read_b128 v[168:171], v233 offset:36864
	ds_read_b128 v[172:175], v233 offset:37888
	ds_read_b128 v[176:179], v233 offset:38912
	ds_read_b128 v[180:183], v233 offset:39936
	global_load_lds_dwordx4 v[190:191], off
	v_lshl_add_u64 v[190:191], s[72:73], 0, v[2:3]
	s_mov_b32 m0, s20
	s_nop 0
	global_load_lds_dwordx4 v[190:191], off
	s_waitcnt lgkmcnt(8)
	s_barrier
	s_waitcnt lgkmcnt(0)
	s_waitcnt lgkmcnt(0)
	v_mfma_f32_16x16x32_bf16 v[132:135], v[136:139], v[152:155], v[132:135]
	v_mfma_f32_16x16x32_bf16 v[128:131], v[144:147], v[152:155], v[128:131]
	v_mfma_f32_16x16x32_bf16 v[116:119], v[136:139], v[160:163], v[116:119]
	v_mfma_f32_16x16x32_bf16 v[112:115], v[144:147], v[160:163], v[112:115]
	v_mfma_f32_16x16x32_bf16 v[100:103], v[136:139], v[168:171], v[100:103]
	v_mfma_f32_16x16x32_bf16 v[96:99], v[144:147], v[168:171], v[96:99]
	v_mfma_f32_16x16x32_bf16 v[84:87], v[136:139], v[176:179], v[84:87]
	v_mfma_f32_16x16x32_bf16 v[80:83], v[144:147], v[176:179], v[80:83]
	v_mfma_f32_16x16x32_bf16 v[132:135], v[140:143], v[156:159], v[132:135]
	v_mfma_f32_16x16x32_bf16 v[128:131], v[148:151], v[156:159], v[128:131]
	v_mfma_f32_16x16x32_bf16 v[116:119], v[140:143], v[164:167], v[116:119]
	v_mfma_f32_16x16x32_bf16 v[112:115], v[148:151], v[164:167], v[112:115]
	v_mfma_f32_16x16x32_bf16 v[100:103], v[140:143], v[172:175], v[100:103]
	v_mfma_f32_16x16x32_bf16 v[96:99], v[148:151], v[172:175], v[96:99]
	v_mfma_f32_16x16x32_bf16 v[84:87], v[140:143], v[180:183], v[84:87]
	v_mfma_f32_16x16x32_bf16 v[80:83], v[148:151], v[180:183], v[80:83]
	s_barrier
	s_add_i32 s31, 0, 0x1c000
	s_add_i32 s8, s8, s33
	v_add_u32_e32 v234, s31, v231
	v_lshl_add_u64 v[218:219], v[218:219], 0, s[12:13]
	s_mov_b32 m0, s8
	ds_read_b128 v[190:193], v234
	ds_read_b128 v[194:197], v234 offset:1024
	ds_read_b128 v[198:201], v234 offset:2048
	ds_read_b128 v[234:237], v234 offset:3072
	global_load_lds_dwordx4 v[218:219], off
	v_lshl_add_u64 v[218:219], v[238:239], 0, s[12:13]
	s_add_i32 m0, s8, 0x2000
	s_nop 0
	global_load_lds_dwordx4 v[218:219], off
	s_barrier
; #define PG8_STAGE(bufoff, gbase, voff) do { _Pragma("unroll") for (int _i = 0; _i < 2; ++_i) \
;         __builtin_amdgcn_global_load_lds((const unsigned*)((const char*)(gbase) + (voff)[_i]), (LAS unsigned*)(lds + (bufoff) + ldsw + _i * 8192), 16, 0, 0); } while (0)
; #define PG8_LDA(dst, b, h) do { _Pragma("unroll") for (int m = 0; m < 4; ++m) _Pragma("unroll") for (int k = 0; k < 2; ++k) dst[m][k] = *(const LAS bf16x8*)(lds + PG8_SA(b, h) + aoff + m * 2048 + k * 1024); } while (0)
; #define PG8_LDB(dst, b, h) do { _Pragma("unroll") for (int n = 0; n < 2; ++n) _Pragma("unroll") for (int k = 0; k < 2; ++k) dst[n][k] = *(const LAS bf16x8*)(lds + PG8_SB(b, h) + boff + n * 2048 + k * 1024); } while (0)
; #define PG8_MMA(ai, bj, At, Bt) do { __builtin_amdgcn_s_setprio(1); _Pragma("unroll") for (int m = 0; m < 4; ++m) _Pragma("unroll") for (int n = 0; n < 2; ++n) _Pragma("unroll") for (int k = 0; k < 2; ++k) \
;         acc[ai][bj][m][n] = __builtin_amdgcn_mfma_f32_16x16x32_bf16(Bt[n][k], At[m][k], acc[ai][bj][m][n], 0, 0, 0); __builtin_amdgcn_s_setprio(0); } while (0)
; #define PG8_WAIT_V(n) asm volatile("s_waitcnt vmcnt(" #n ")" ::: "memory")
; #define PG8_WAIT_L(n) asm volatile("s_waitcnt lgkmcnt(" #n ")" ::: "memory")
; #define PG8_BAR __builtin_amdgcn_s_barrier()
; #define PG8_SCHED __builtin_amdgcn_sched_barrier(0)
; template <class Epi>
; __device__ __forceinline__ void gemm_phase(LAS unsigned char* lds, const Gemm g, const StaticOrder& S, const Epi& E) {
;     ...
;             PG8_WAIT_L(8); PG8_BAR; PG8_WAIT_L(0); PG8_MMA(0, 0, At, B0); PG8_BAR; PG8_SCHED;
;             PG8_LDB(B1, 1, 1); PG8_STAGE(PG8_SB(1, 0), b3, voffB);
;             PG8_BAR; PG8_WAIT_L(0); PG8_MMA(0, 1, At, B1); PG8_BAR;
;             PG8_LDA(At, 1, 1); PG8_STAGE(PG8_SA(1, 0), a3, voffA);
;             PG8_BAR; PG8_WAIT_L(0); PG8_MMA(1, 0, At, B0); PG8_BAR; PG8_SCHED;
;             PG8_STAGE(PG8_SB(1, 1), b3 + hstep, voffB);
;             PG8_WAIT_V(6); PG8_BAR; PG8_MMA(1, 1, At, B1); PG8_BAR;
;         }
	s_waitcnt lgkmcnt(0)
	s_waitcnt lgkmcnt(0)
	v_mfma_f32_16x16x32_bf16 v[124:127], v[190:193], v[152:155], v[124:127]
	v_mfma_f32_16x16x32_bf16 v[120:123], v[198:201], v[152:155], v[120:123]
	v_mfma_f32_16x16x32_bf16 v[108:111], v[190:193], v[160:163], v[108:111]
	v_mfma_f32_16x16x32_bf16 v[104:107], v[198:201], v[160:163], v[104:107]
	v_mfma_f32_16x16x32_bf16 v[92:95], v[190:193], v[168:171], v[92:95]
	v_mfma_f32_16x16x32_bf16 v[88:91], v[198:201], v[168:171], v[88:91]
	v_mfma_f32_16x16x32_bf16 v[76:79], v[190:193], v[176:179], v[76:79]
	v_mfma_f32_16x16x32_bf16 v[72:75], v[198:201], v[176:179], v[72:75]
	v_mfma_f32_16x16x32_bf16 v[124:127], v[194:197], v[156:159], v[124:127]
	v_mfma_f32_16x16x32_bf16 v[120:123], v[234:237], v[156:159], v[120:123]
	v_mfma_f32_16x16x32_bf16 v[108:111], v[194:197], v[164:167], v[108:111]
	v_mfma_f32_16x16x32_bf16 v[104:107], v[234:237], v[164:167], v[104:107]
	v_mfma_f32_16x16x32_bf16 v[92:95], v[194:197], v[172:175], v[92:95]
	v_mfma_f32_16x16x32_bf16 v[88:91], v[234:237], v[172:175], v[88:91]
	v_mfma_f32_16x16x32_bf16 v[76:79], v[194:197], v[180:183], v[76:79]
	v_mfma_f32_16x16x32_bf16 v[72:75], v[234:237], v[180:183], v[72:75]
	s_mov_b32 m0, s24
	v_lshl_add_u64 v[218:219], v[240:241], 0, s[12:13]
	s_barrier
	ds_read_b128 v[152:155], v233 offset:49152
	ds_read_b128 v[156:159], v233 offset:50176
	ds_read_b128 v[160:163], v233 offset:51200
	ds_read_b128 v[164:167], v233 offset:52224
	ds_read_b128 v[168:171], v233 offset:53248
	ds_read_b128 v[172:175], v233 offset:54272
	ds_read_b128 v[176:179], v233 offset:55296
	ds_read_b128 v[180:183], v233 offset:56320
	global_load_lds_dwordx4 v[218:219], off
	v_lshl_add_u64 v[218:219], v[242:243], 0, s[12:13]
	s_mov_b32 m0, s25
	s_nop 0
	global_load_lds_dwordx4 v[218:219], off
	s_barrier
	s_waitcnt lgkmcnt(0)
	s_waitcnt lgkmcnt(0)
	v_mfma_f32_16x16x32_bf16 v[68:71], v[136:139], v[152:155], v[68:71]
	v_mfma_f32_16x16x32_bf16 v[64:67], v[144:147], v[152:155], v[64:67]
	v_mfma_f32_16x16x32_bf16 v[52:55], v[136:139], v[160:163], v[52:55]
	v_mfma_f32_16x16x32_bf16 v[48:51], v[144:147], v[160:163], v[48:51]
	v_mfma_f32_16x16x32_bf16 v[36:39], v[136:139], v[168:171], v[36:39]
	v_mfma_f32_16x16x32_bf16 v[32:35], v[144:147], v[168:171], v[32:35]
	v_mfma_f32_16x16x32_bf16 v[20:23], v[136:139], v[176:179], v[20:23]
	v_mfma_f32_16x16x32_bf16 v[16:19], v[144:147], v[176:179], v[16:19]
	v_mfma_f32_16x16x32_bf16 v[68:71], v[140:143], v[156:159], v[68:71]
	v_mfma_f32_16x16x32_bf16 v[64:67], v[148:151], v[156:159], v[64:67]
	v_mfma_f32_16x16x32_bf16 v[52:55], v[140:143], v[164:167], v[52:55]
	v_mfma_f32_16x16x32_bf16 v[48:51], v[148:151], v[164:167], v[48:51]
	v_mfma_f32_16x16x32_bf16 v[36:39], v[140:143], v[172:175], v[36:39]
	v_mfma_f32_16x16x32_bf16 v[32:35], v[148:151], v[172:175], v[32:35]
	v_mfma_f32_16x16x32_bf16 v[20:23], v[140:143], v[180:183], v[20:23]
	v_mfma_f32_16x16x32_bf16 v[16:19], v[148:151], v[180:183], v[16:19]
	s_barrier
	s_add_u32 s72, s94, 0x40080
	s_addc_u32 s73, s95, 0
	s_add_i32 s8, s31, s33
	v_lshl_add_u64 v[136:137], s[72:73], 0, v[0:1]
	s_mov_b32 m0, s8
	s_nop 0
	global_load_lds_dwordx4 v[136:137], off
	v_lshl_add_u64 v[136:137], s[72:73], 0, v[2:3]
	s_add_i32 m0, s8, 0x2000
	s_nop 0
	global_load_lds_dwordx4 v[136:137], off
	s_waitcnt vmcnt(6)
	s_barrier
	v_mfma_f32_16x16x32_bf16 v[60:63], v[190:193], v[152:155], v[60:63]
	v_mfma_f32_16x16x32_bf16 v[56:59], v[198:201], v[152:155], v[56:59]
	v_mfma_f32_16x16x32_bf16 v[44:47], v[190:193], v[160:163], v[44:47]
	v_mfma_f32_16x16x32_bf16 v[40:43], v[198:201], v[160:163], v[40:43]
	v_mfma_f32_16x16x32_bf16 v[28:31], v[190:193], v[168:171], v[28:31]
	v_mfma_f32_16x16x32_bf16 v[24:27], v[198:201], v[168:171], v[24:27]
	v_mfma_f32_16x16x32_bf16 v[12:15], v[190:193], v[176:179], v[12:15]
	v_mfma_f32_16x16x32_bf16 v[8:11], v[198:201], v[176:179], v[8:11]
	v_mfma_f32_16x16x32_bf16 v[60:63], v[194:197], v[156:159], v[60:63]
	v_mfma_f32_16x16x32_bf16 v[56:59], v[234:237], v[156:159], v[56:59]
	v_mfma_f32_16x16x32_bf16 v[44:47], v[194:197], v[164:167], v[44:47]
	v_mfma_f32_16x16x32_bf16 v[40:43], v[234:237], v[164:167], v[40:43]
	v_mfma_f32_16x16x32_bf16 v[28:31], v[194:197], v[172:175], v[28:31]
	v_mfma_f32_16x16x32_bf16 v[24:27], v[234:237], v[172:175], v[24:27]
	v_mfma_f32_16x16x32_bf16 v[12:15], v[194:197], v[180:183], v[12:15]
	v_mfma_f32_16x16x32_bf16 v[8:11], v[234:237], v[180:183], v[8:11]
	s_add_u32 s96, s96, 0x100
	s_addc_u32 s97, s97, 0
	s_cmp_ge_i32 s30, s90
	s_mov_b64 s[72:73], s[74:75]
	s_mov_b32 s94, s30
	s_barrier
	s_cbranch_scc0 .LBB0_1489
	s_mov_b64 s[96:97], s[50:51]
	s_branch .LBB0_1492

; #define PG8_WAIT_V(n) asm volatile("s_waitcnt vmcnt(" #n ")" ::: "memory")
; #define PG8_BAR __builtin_amdgcn_s_barrier()
; template <class Epi>
; __device__ __forceinline__ void gemm_phase(LAS unsigned char* lds, const Gemm g, const StaticOrder& S, const Epi& E) {
;     ...
;     PG8_WAIT_V(0);
;     if (wr == 0) PG8_BAR;
;     PG8_BAR;
.LBB0_1561:
	s_setprio 0
	s_waitcnt vmcnt(0)
	s_cmpk_gt_u32 s3, 0xff
	v_readlane_b32 s78, v255, 24
	s_mov_b32 s87, 0x8000
	s_cbranch_scc1 .LBB0_1563
	s_barrier

; #define PG8_STAGE(bufoff, gbase, voff) do { _Pragma("unroll") for (int _i = 0; _i < 2; ++_i) \
;         __builtin_amdgcn_global_load_lds((const unsigned*)((const char*)(gbase) + (voff)[_i]), (LAS unsigned*)(lds + (bufoff) + ldsw + _i * 8192), 16, 0, 0); } while (0)
; #define PG8_LDA(dst, b, h) do { _Pragma("unroll") for (int m = 0; m < 4; ++m) _Pragma("unroll") for (int k = 0; k < 2; ++k) dst[m][k] = *(const LAS bf16x8*)(lds + PG8_SA(b, h) + aoff + m * 2048 + k * 1024); } while (0)
; #define PG8_LDB(dst, b, h) do { _Pragma("unroll") for (int n = 0; n < 2; ++n) _Pragma("unroll") for (int k = 0; k < 2; ++k) dst[n][k] = *(const LAS bf16x8*)(lds + PG8_SB(b, h) + boff + n * 2048 + k * 1024); } while (0)
; #define PG8_MMA(ai, bj, At, Bt) do { __builtin_amdgcn_s_setprio(1); _Pragma("unroll") for (int m = 0; m < 4; ++m) _Pragma("unroll") for (int n = 0; n < 2; ++n) _Pragma("unroll") for (int k = 0; k < 2; ++k) \
;         acc[ai][bj][m][n] = __builtin_amdgcn_mfma_f32_16x16x32_bf16(Bt[n][k], At[m][k], acc[ai][bj][m][n], 0, 0, 0); __builtin_amdgcn_s_setprio(0); } while (0)
; #define PG8_WAIT_L(n) asm volatile("s_waitcnt lgkmcnt(" #n ")" ::: "memory")
; #define PG8_BAR __builtin_amdgcn_s_barrier()
; #define PG8_SCHED __builtin_amdgcn_sched_barrier(0)
; template <class Epi>
; __device__ __forceinline__ void gemm_phase(LAS unsigned char* lds, const Gemm g, const StaticOrder& S, const Epi& E) {
;     ...
;             const bool last = (t == nt - 2);
;             const char* a1 = cA + (size_t)(t + 1) * kstep;
;             const char* a2 = last ? nA : cA + (size_t)(t + 2) * kstep; const char* b2 = last ? nB : cB + (size_t)(t + 2) * kstep;
;             const char* a3 = a2 + kstep; const char* b3 = b2 + kstep;
;             PG8_LDB(B0, 0, 0); PG8_SCHED; PG8_LDA(At, 0, 0); PG8_STAGE(PG8_SA(1, 1), a1 + hstep, voffA);
;             PG8_WAIT_L(8); PG8_BAR; PG8_WAIT_L(0); PG8_MMA(0, 0, At, B0); PG8_BAR; PG8_SCHED;
;             PG8_LDB(B1, 0, 1); PG8_STAGE(PG8_SB(0, 0), b2, voffB);
;             PG8_BAR; PG8_WAIT_L(0); PG8_MMA(0, 1, At, B1); PG8_BAR;
;             PG8_LDA(At, 0, 1); PG8_STAGE(PG8_SA(0, 0), a2, voffA);
;             PG8_BAR; PG8_WAIT_L(0); PG8_MMA(1, 0, At, B0); PG8_BAR; PG8_SCHED;
.LBB0_1766:
	s_add_i32 s33, s29, 2
	s_add_u32 s8, s58, 0xfffc0080
	s_addc_u32 s45, s59, -1
	s_add_i32 s47, 0, 0x10000
	v_add_u32_e32 v160, s47, v145
	ds_read_b128 v[148:151], v160
	ds_read_b128 v[152:155], v160 offset:1024
	ds_read_b128 v[156:159], v160 offset:2048
	ds_read_b128 v[160:163], v160 offset:3072
	s_cmp_eq_u32 s23, s29
	s_cselect_b32 s63, s4, s45
	s_cselect_b32 s62, s5, s8
	s_cselect_b32 s61, s21, s25
	s_cselect_b32 s60, s22, s24
	v_lshl_add_u64 v[198:199], s[58:59], 0, v[142:143]
	s_add_i32 m0, s57, 0xc000
	ds_read_b128 v[164:167], v147
	ds_read_b128 v[168:171], v147 offset:1024
	ds_read_b128 v[172:175], v147 offset:2048
	ds_read_b128 v[176:179], v147 offset:3072
	ds_read_b128 v[180:183], v147 offset:4096
	ds_read_b128 v[186:189], v147 offset:5120
	ds_read_b128 v[190:193], v147 offset:6144
	ds_read_b128 v[194:197], v147 offset:7168
	global_load_lds_dwordx4 v[198:199], off
	v_lshl_add_u64 v[198:199], s[58:59], 0, v[140:141]
	s_add_i32 m0, s57, 0xe000
	s_nop 0
	global_load_lds_dwordx4 v[198:199], off
	s_waitcnt lgkmcnt(8)
	s_barrier
	s_waitcnt lgkmcnt(0)
	s_waitcnt lgkmcnt(0)
	v_mfma_f32_16x16x32_bf16 v[132:135], v[148:151], v[164:167], v[132:135]
	v_mfma_f32_16x16x32_bf16 v[124:127], v[156:159], v[164:167], v[124:127]
	v_mfma_f32_16x16x32_bf16 v[116:119], v[148:151], v[172:175], v[116:119]
	v_mfma_f32_16x16x32_bf16 v[108:111], v[156:159], v[172:175], v[108:111]
	v_mfma_f32_16x16x32_bf16 v[100:103], v[148:151], v[180:183], v[100:103]
	v_mfma_f32_16x16x32_bf16 v[92:95], v[156:159], v[180:183], v[92:95]
	v_mfma_f32_16x16x32_bf16 v[84:87], v[148:151], v[190:193], v[84:87]
	v_mfma_f32_16x16x32_bf16 v[76:79], v[156:159], v[190:193], v[76:79]
	v_mfma_f32_16x16x32_bf16 v[132:135], v[152:155], v[168:171], v[132:135]
	v_mfma_f32_16x16x32_bf16 v[124:127], v[160:163], v[168:171], v[124:127]
	v_mfma_f32_16x16x32_bf16 v[116:119], v[152:155], v[176:179], v[116:119]
	v_mfma_f32_16x16x32_bf16 v[108:111], v[160:163], v[176:179], v[108:111]
	v_mfma_f32_16x16x32_bf16 v[100:103], v[152:155], v[186:189], v[100:103]
	v_mfma_f32_16x16x32_bf16 v[92:95], v[160:163], v[186:189], v[92:95]
	v_mfma_f32_16x16x32_bf16 v[84:87], v[152:155], v[194:197], v[84:87]
	v_mfma_f32_16x16x32_bf16 v[76:79], v[160:163], v[194:197], v[76:79]
	s_barrier
	s_add_i32 s8, 0, 0x14000
	s_add_i32 s29, s47, s66
	v_add_u32_e32 v185, s8, v145
	v_lshl_add_u64 v[218:219], s[60:61], 0, v[0:1]
	s_mov_b32 m0, s29
	ds_read_b128 v[198:201], v185
	ds_read_b128 v[232:235], v185 offset:1024
	ds_read_b128 v[236:239], v185 offset:2048
	ds_read_b128 v[240:243], v185 offset:3072
	global_load_lds_dwordx4 v[218:219], off
	v_lshl_add_u64 v[244:245], s[60:61], 0, v[2:3]
	s_add_i32 m0, s29, 0x2000
	s_nop 0
	global_load_lds_dwordx4 v[244:245], off
	s_barrier
	s_waitcnt lgkmcnt(0)
	s_waitcnt lgkmcnt(0)
	v_mfma_f32_16x16x32_bf16 v[128:131], v[198:201], v[164:167], v[128:131]
	v_mfma_f32_16x16x32_bf16 v[120:123], v[236:239], v[164:167], v[120:123]
	v_mfma_f32_16x16x32_bf16 v[112:115], v[198:201], v[172:175], v[112:115]
	v_mfma_f32_16x16x32_bf16 v[104:107], v[236:239], v[172:175], v[104:107]
	v_mfma_f32_16x16x32_bf16 v[96:99], v[198:201], v[180:183], v[96:99]
	v_mfma_f32_16x16x32_bf16 v[88:91], v[236:239], v[180:183], v[88:91]
	v_mfma_f32_16x16x32_bf16 v[80:83], v[198:201], v[190:193], v[80:83]
	v_mfma_f32_16x16x32_bf16 v[72:75], v[236:239], v[190:193], v[72:75]
	v_mfma_f32_16x16x32_bf16 v[128:131], v[232:235], v[168:171], v[128:131]
	v_mfma_f32_16x16x32_bf16 v[120:123], v[240:243], v[168:171], v[120:123]
	v_mfma_f32_16x16x32_bf16 v[112:115], v[232:235], v[176:179], v[112:115]
	v_mfma_f32_16x16x32_bf16 v[104:107], v[240:243], v[176:179], v[104:107]
	v_mfma_f32_16x16x32_bf16 v[96:99], v[232:235], v[186:189], v[96:99]
	v_mfma_f32_16x16x32_bf16 v[88:91], v[240:243], v[186:189], v[88:91]
	v_mfma_f32_16x16x32_bf16 v[80:83], v[232:235], v[194:197], v[80:83]
	v_mfma_f32_16x16x32_bf16 v[72:75], v[240:243], v[194:197], v[72:75]
	s_mov_b32 m0, s57
	v_lshl_add_u64 v[246:247], s[62:63], 0, v[138:139]
	s_barrier
	ds_read_b128 v[164:167], v147 offset:16384
	ds_read_b128 v[168:171], v147 offset:17408
	ds_read_b128 v[172:175], v147 offset:18432
	ds_read_b128 v[176:179], v147 offset:19456
	ds_read_b128 v[180:183], v147 offset:20480
	ds_read_b128 v[186:189], v147 offset:21504
	ds_read_b128 v[190:193], v147 offset:22528
	ds_read_b128 v[194:197], v147 offset:23552
	global_load_lds_dwordx4 v[246:247], off
	v_lshl_add_u64 v[248:249], s[62:63], 0, v[136:137]
	s_mov_b32 m0, s67
	s_nop 0
	global_load_lds_dwordx4 v[248:249], off
	s_barrier
	s_waitcnt lgkmcnt(0)
	s_waitcnt lgkmcnt(0)
	v_mfma_f32_16x16x32_bf16 v[68:71], v[148:151], v[164:167], v[68:71]
	v_mfma_f32_16x16x32_bf16 v[60:63], v[156:159], v[164:167], v[60:63]
	v_mfma_f32_16x16x32_bf16 v[52:55], v[148:151], v[172:175], v[52:55]
	v_mfma_f32_16x16x32_bf16 v[44:47], v[156:159], v[172:175], v[44:47]
	v_mfma_f32_16x16x32_bf16 v[36:39], v[148:151], v[180:183], v[36:39]
	v_mfma_f32_16x16x32_bf16 v[28:31], v[156:159], v[180:183], v[28:31]
	v_mfma_f32_16x16x32_bf16 v[20:23], v[148:151], v[190:193], v[20:23]
	v_mfma_f32_16x16x32_bf16 v[12:15], v[156:159], v[190:193], v[12:15]
	v_mfma_f32_16x16x32_bf16 v[68:71], v[152:155], v[168:171], v[68:71]
	v_mfma_f32_16x16x32_bf16 v[60:63], v[160:163], v[168:171], v[60:63]
	v_mfma_f32_16x16x32_bf16 v[52:55], v[152:155], v[176:179], v[52:55]
	v_mfma_f32_16x16x32_bf16 v[44:47], v[160:163], v[176:179], v[44:47]
	v_mfma_f32_16x16x32_bf16 v[36:39], v[152:155], v[186:189], v[36:39]
	v_mfma_f32_16x16x32_bf16 v[28:31], v[160:163], v[186:189], v[28:31]
	v_mfma_f32_16x16x32_bf16 v[20:23], v[152:155], v[194:197], v[20:23]
	v_mfma_f32_16x16x32_bf16 v[12:15], v[160:163], v[194:197], v[12:15]
	s_barrier
; #define PG8_STAGE(bufoff, gbase, voff) do { _Pragma("unroll") for (int _i = 0; _i < 2; ++_i) \
;         __builtin_amdgcn_global_load_lds((const unsigned*)((const char*)(gbase) + (voff)[_i]), (LAS unsigned*)(lds + (bufoff) + ldsw + _i * 8192), 16, 0, 0); } while (0)
; #define PG8_LDA(dst, b, h) do { _Pragma("unroll") for (int m = 0; m < 4; ++m) _Pragma("unroll") for (int k = 0; k < 2; ++k) dst[m][k] = *(const LAS bf16x8*)(lds + PG8_SA(b, h) + aoff + m * 2048 + k * 1024); } while (0)
; #define PG8_LDB(dst, b, h) do { _Pragma("unroll") for (int n = 0; n < 2; ++n) _Pragma("unroll") for (int k = 0; k < 2; ++k) dst[n][k] = *(const LAS bf16x8*)(lds + PG8_SB(b, h) + boff + n * 2048 + k * 1024); } while (0)
; #define PG8_MMA(ai, bj, At, Bt) do { __builtin_amdgcn_s_setprio(1); _Pragma("unroll") for (int m = 0; m < 4; ++m) _Pragma("unroll") for (int n = 0; n < 2; ++n) _Pragma("unroll") for (int k = 0; k < 2; ++k) \
;         acc[ai][bj][m][n] = __builtin_amdgcn_mfma_f32_16x16x32_bf16(Bt[n][k], At[m][k], acc[ai][bj][m][n], 0, 0, 0); __builtin_amdgcn_s_setprio(0); } while (0)
; #define PG8_WAIT_V(n) asm volatile("s_waitcnt vmcnt(" #n ")" ::: "memory")
; #define PG8_WAIT_L(n) asm volatile("s_waitcnt lgkmcnt(" #n ")" ::: "memory")
; #define PG8_BAR __builtin_amdgcn_s_barrier()
; #define PG8_SCHED __builtin_amdgcn_sched_barrier(0)
; template <class Epi>
; __device__ __forceinline__ void gemm_phase(LAS unsigned char* lds, const Gemm g, const StaticOrder& S, const Epi& E) {
;     ...
;             PG8_STAGE(PG8_SB(0, 1), b2 + hstep, voffB);
;             PG8_WAIT_V(6); PG8_BAR; PG8_MMA(1, 1, At, B1); PG8_BAR;
;             PG8_LDB(B0, 1, 0); PG8_SCHED; PG8_LDA(At, 1, 0); PG8_STAGE(PG8_SA(0, 1), a2 + hstep, voffA);
;             PG8_WAIT_L(8); PG8_BAR; PG8_WAIT_L(0); PG8_MMA(0, 0, At, B0); PG8_BAR; PG8_SCHED;
;             PG8_LDB(B1, 1, 1); PG8_STAGE(PG8_SB(1, 0), b3, voffB);
;             PG8_BAR; PG8_WAIT_L(0); PG8_MMA(0, 1, At, B1); PG8_BAR;
	s_add_u32 s70, s60, 0x40000
	s_addc_u32 s71, s61, 0
	s_add_i32 s8, s8, s66
	v_lshl_add_u64 v[148:149], s[70:71], 0, v[0:1]
	s_mov_b32 m0, s8
	s_nop 0
	global_load_lds_dwordx4 v[148:149], off
	v_lshl_add_u64 v[148:149], s[70:71], 0, v[2:3]
	s_add_i32 m0, s8, 0x2000
	s_nop 0
	global_load_lds_dwordx4 v[148:149], off
	s_waitcnt vmcnt(6)
	s_barrier
	v_mfma_f32_16x16x32_bf16 v[64:67], v[198:201], v[164:167], v[64:67]
	v_mfma_f32_16x16x32_bf16 v[56:59], v[236:239], v[164:167], v[56:59]
	v_mfma_f32_16x16x32_bf16 v[48:51], v[198:201], v[172:175], v[48:51]
	v_mfma_f32_16x16x32_bf16 v[40:43], v[236:239], v[172:175], v[40:43]
	v_mfma_f32_16x16x32_bf16 v[32:35], v[198:201], v[180:183], v[32:35]
	v_mfma_f32_16x16x32_bf16 v[24:27], v[236:239], v[180:183], v[24:27]
	v_mfma_f32_16x16x32_bf16 v[16:19], v[198:201], v[190:193], v[16:19]
	v_mfma_f32_16x16x32_bf16 v[8:11], v[236:239], v[190:193], v[8:11]
	v_mfma_f32_16x16x32_bf16 v[64:67], v[232:235], v[168:171], v[64:67]
	v_mfma_f32_16x16x32_bf16 v[56:59], v[240:243], v[168:171], v[56:59]
	v_mfma_f32_16x16x32_bf16 v[48:51], v[232:235], v[176:179], v[48:51]
	v_mfma_f32_16x16x32_bf16 v[40:43], v[240:243], v[176:179], v[40:43]
	v_mfma_f32_16x16x32_bf16 v[32:35], v[232:235], v[186:189], v[32:35]
	v_mfma_f32_16x16x32_bf16 v[24:27], v[240:243], v[186:189], v[24:27]
	v_mfma_f32_16x16x32_bf16 v[16:19], v[232:235], v[194:197], v[16:19]
	v_mfma_f32_16x16x32_bf16 v[8:11], v[240:243], v[194:197], v[8:11]
	s_add_i32 s8, 0, 0x18000
	v_add_u32_e32 v160, s8, v145
	s_barrier
	ds_read_b128 v[148:151], v160
	ds_read_b128 v[152:155], v160 offset:1024
	ds_read_b128 v[156:159], v160 offset:2048
	ds_read_b128 v[160:163], v160 offset:3072
	s_add_u32 s62, s62, 0x40000
	s_addc_u32 s63, s63, 0
	s_mov_b32 m0, s68
	v_lshl_add_u64 v[198:199], s[62:63], 0, v[138:139]
	ds_read_b128 v[164:167], v147 offset:32768
	ds_read_b128 v[168:171], v147 offset:33792
	ds_read_b128 v[172:175], v147 offset:34816
	ds_read_b128 v[176:179], v147 offset:35840
	ds_read_b128 v[180:183], v147 offset:36864
	ds_read_b128 v[186:189], v147 offset:37888
	ds_read_b128 v[190:193], v147 offset:38912
	ds_read_b128 v[194:197], v147 offset:39936
	global_load_lds_dwordx4 v[198:199], off
	v_lshl_add_u64 v[198:199], s[62:63], 0, v[136:137]
	s_mov_b32 m0, s69
	s_nop 0
	global_load_lds_dwordx4 v[198:199], off
	s_waitcnt lgkmcnt(8)
	s_barrier
	s_waitcnt lgkmcnt(0)
	s_waitcnt lgkmcnt(0)
	v_mfma_f32_16x16x32_bf16 v[132:135], v[148:151], v[164:167], v[132:135]
	v_mfma_f32_16x16x32_bf16 v[124:127], v[156:159], v[164:167], v[124:127]
	v_mfma_f32_16x16x32_bf16 v[116:119], v[148:151], v[172:175], v[116:119]
	v_mfma_f32_16x16x32_bf16 v[108:111], v[156:159], v[172:175], v[108:111]
	v_mfma_f32_16x16x32_bf16 v[100:103], v[148:151], v[180:183], v[100:103]
	v_mfma_f32_16x16x32_bf16 v[92:95], v[156:159], v[180:183], v[92:95]
	v_mfma_f32_16x16x32_bf16 v[84:87], v[148:151], v[190:193], v[84:87]
	v_mfma_f32_16x16x32_bf16 v[76:79], v[156:159], v[190:193], v[76:79]
	v_mfma_f32_16x16x32_bf16 v[132:135], v[152:155], v[168:171], v[132:135]
	v_mfma_f32_16x16x32_bf16 v[124:127], v[160:163], v[168:171], v[124:127]
	v_mfma_f32_16x16x32_bf16 v[116:119], v[152:155], v[176:179], v[116:119]
	v_mfma_f32_16x16x32_bf16 v[108:111], v[160:163], v[176:179], v[108:111]
	v_mfma_f32_16x16x32_bf16 v[100:103], v[152:155], v[186:189], v[100:103]
	v_mfma_f32_16x16x32_bf16 v[92:95], v[160:163], v[186:189], v[92:95]
	v_mfma_f32_16x16x32_bf16 v[84:87], v[152:155], v[194:197], v[84:87]
	v_mfma_f32_16x16x32_bf16 v[76:79], v[160:163], v[194:197], v[76:79]
	s_barrier
	s_add_i32 s29, 0, 0x1c000
	s_add_i32 s8, s8, s66
	v_add_u32_e32 v185, s29, v145
	v_lshl_add_u64 v[218:219], v[218:219], 0, s[12:13]
	s_mov_b32 m0, s8
	ds_read_b128 v[198:201], v185
	ds_read_b128 v[232:235], v185 offset:1024
	ds_read_b128 v[236:239], v185 offset:2048
	ds_read_b128 v[240:243], v185 offset:3072
	global_load_lds_dwordx4 v[218:219], off
	v_lshl_add_u64 v[218:219], v[244:245], 0, s[12:13]
	s_add_i32 m0, s8, 0x2000
	s_nop 0
	global_load_lds_dwordx4 v[218:219], off
	s_barrier
; #define PG8_STAGE(bufoff, gbase, voff) do { _Pragma("unroll") for (int _i = 0; _i < 2; ++_i) \
;         __builtin_amdgcn_global_load_lds((const unsigned*)((const char*)(gbase) + (voff)[_i]), (LAS unsigned*)(lds + (bufoff) + ldsw + _i * 8192), 16, 0, 0); } while (0)
; #define PG8_LDA(dst, b, h) do { _Pragma("unroll") for (int m = 0; m < 4; ++m) _Pragma("unroll") for (int k = 0; k < 2; ++k) dst[m][k] = *(const LAS bf16x8*)(lds + PG8_SA(b, h) + aoff + m * 2048 + k * 1024); } while (0)
; #define PG8_MMA(ai, bj, At, Bt) do { __builtin_amdgcn_s_setprio(1); _Pragma("unroll") for (int m = 0; m < 4; ++m) _Pragma("unroll") for (int n = 0; n < 2; ++n) _Pragma("unroll") for (int k = 0; k < 2; ++k) \
;         acc[ai][bj][m][n] = __builtin_amdgcn_mfma_f32_16x16x32_bf16(Bt[n][k], At[m][k], acc[ai][bj][m][n], 0, 0, 0); __builtin_amdgcn_s_setprio(0); } while (0)
; #define PG8_WAIT_V(n) asm volatile("s_waitcnt vmcnt(" #n ")" ::: "memory")
; #define PG8_WAIT_L(n) asm volatile("s_waitcnt lgkmcnt(" #n ")" ::: "memory")
; #define PG8_BAR __builtin_amdgcn_s_barrier()
; #define PG8_SCHED __builtin_amdgcn_sched_barrier(0)
; template <class Epi>
; __device__ __forceinline__ void gemm_phase(LAS unsigned char* lds, const Gemm g, const StaticOrder& S, const Epi& E) {
;     ...
;             PG8_BAR; PG8_WAIT_L(0); PG8_MMA(0, 1, At, B1); PG8_BAR;
;             PG8_LDA(At, 1, 1); PG8_STAGE(PG8_SA(1, 0), a3, voffA);
;             PG8_BAR; PG8_WAIT_L(0); PG8_MMA(1, 0, At, B0); PG8_BAR; PG8_SCHED;
;             PG8_STAGE(PG8_SB(1, 1), b3 + hstep, voffB);
;             PG8_WAIT_V(6); PG8_BAR; PG8_MMA(1, 1, At, B1); PG8_BAR;
;     ...
;     PG8_WAIT_V(0);
;     if (wr == 0) PG8_BAR;
	s_waitcnt lgkmcnt(0)
	s_waitcnt lgkmcnt(0)
	v_mfma_f32_16x16x32_bf16 v[128:131], v[198:201], v[164:167], v[128:131]
	v_mfma_f32_16x16x32_bf16 v[120:123], v[236:239], v[164:167], v[120:123]
	v_mfma_f32_16x16x32_bf16 v[112:115], v[198:201], v[172:175], v[112:115]
	v_mfma_f32_16x16x32_bf16 v[104:107], v[236:239], v[172:175], v[104:107]
	v_mfma_f32_16x16x32_bf16 v[96:99], v[198:201], v[180:183], v[96:99]
	v_mfma_f32_16x16x32_bf16 v[88:91], v[236:239], v[180:183], v[88:91]
	v_mfma_f32_16x16x32_bf16 v[80:83], v[198:201], v[190:193], v[80:83]
	v_mfma_f32_16x16x32_bf16 v[72:75], v[236:239], v[190:193], v[72:75]
	v_mfma_f32_16x16x32_bf16 v[128:131], v[232:235], v[168:171], v[128:131]
	v_mfma_f32_16x16x32_bf16 v[120:123], v[240:243], v[168:171], v[120:123]
	v_mfma_f32_16x16x32_bf16 v[112:115], v[232:235], v[176:179], v[112:115]
	v_mfma_f32_16x16x32_bf16 v[104:107], v[240:243], v[176:179], v[104:107]
	v_mfma_f32_16x16x32_bf16 v[96:99], v[232:235], v[186:189], v[96:99]
	v_mfma_f32_16x16x32_bf16 v[88:91], v[240:243], v[186:189], v[88:91]
	v_mfma_f32_16x16x32_bf16 v[80:83], v[232:235], v[194:197], v[80:83]
	v_mfma_f32_16x16x32_bf16 v[72:75], v[240:243], v[194:197], v[72:75]
	s_mov_b32 m0, s6
	v_lshl_add_u64 v[218:219], v[246:247], 0, s[12:13]
	s_barrier
	ds_read_b128 v[164:167], v147 offset:49152
	ds_read_b128 v[168:171], v147 offset:50176
	ds_read_b128 v[172:175], v147 offset:51200
	ds_read_b128 v[176:179], v147 offset:52224
	ds_read_b128 v[180:183], v147 offset:53248
	ds_read_b128 v[186:189], v147 offset:54272
	ds_read_b128 v[190:193], v147 offset:55296
	ds_read_b128 v[194:197], v147 offset:56320
	global_load_lds_dwordx4 v[218:219], off
	v_lshl_add_u64 v[218:219], v[248:249], 0, s[12:13]
	s_mov_b32 m0, s18
	s_nop 0
	global_load_lds_dwordx4 v[218:219], off
	s_barrier
	s_waitcnt lgkmcnt(0)
	s_waitcnt lgkmcnt(0)
	v_mfma_f32_16x16x32_bf16 v[68:71], v[148:151], v[164:167], v[68:71]
	v_mfma_f32_16x16x32_bf16 v[60:63], v[156:159], v[164:167], v[60:63]
	v_mfma_f32_16x16x32_bf16 v[52:55], v[148:151], v[172:175], v[52:55]
	v_mfma_f32_16x16x32_bf16 v[44:47], v[156:159], v[172:175], v[44:47]
	v_mfma_f32_16x16x32_bf16 v[36:39], v[148:151], v[180:183], v[36:39]
	v_mfma_f32_16x16x32_bf16 v[28:31], v[156:159], v[180:183], v[28:31]
	v_mfma_f32_16x16x32_bf16 v[20:23], v[148:151], v[190:193], v[20:23]
	v_mfma_f32_16x16x32_bf16 v[12:15], v[156:159], v[190:193], v[12:15]
	v_mfma_f32_16x16x32_bf16 v[68:71], v[152:155], v[168:171], v[68:71]
	v_mfma_f32_16x16x32_bf16 v[60:63], v[160:163], v[168:171], v[60:63]
	v_mfma_f32_16x16x32_bf16 v[52:55], v[152:155], v[176:179], v[52:55]
	v_mfma_f32_16x16x32_bf16 v[44:47], v[160:163], v[176:179], v[44:47]
	v_mfma_f32_16x16x32_bf16 v[36:39], v[152:155], v[186:189], v[36:39]
	v_mfma_f32_16x16x32_bf16 v[28:31], v[160:163], v[186:189], v[28:31]
	v_mfma_f32_16x16x32_bf16 v[20:23], v[152:155], v[194:197], v[20:23]
	v_mfma_f32_16x16x32_bf16 v[12:15], v[160:163], v[194:197], v[12:15]
	s_barrier
	s_add_u32 s60, s60, 0x40080
	s_addc_u32 s61, s61, 0
	s_add_i32 s8, s29, s66
	v_lshl_add_u64 v[148:149], s[60:61], 0, v[0:1]
	s_mov_b32 m0, s8
	s_nop 0
	global_load_lds_dwordx4 v[148:149], off
	v_lshl_add_u64 v[148:149], s[60:61], 0, v[2:3]
	s_add_i32 m0, s8, 0x2000
	s_nop 0
	global_load_lds_dwordx4 v[148:149], off
	s_waitcnt vmcnt(6)
	s_barrier
	v_mfma_f32_16x16x32_bf16 v[64:67], v[198:201], v[164:167], v[64:67]
	v_mfma_f32_16x16x32_bf16 v[56:59], v[236:239], v[164:167], v[56:59]
	v_mfma_f32_16x16x32_bf16 v[48:51], v[198:201], v[172:175], v[48:51]
	v_mfma_f32_16x16x32_bf16 v[40:43], v[236:239], v[172:175], v[40:43]
	v_mfma_f32_16x16x32_bf16 v[32:35], v[198:201], v[180:183], v[32:35]
	v_mfma_f32_16x16x32_bf16 v[24:27], v[236:239], v[180:183], v[24:27]
	v_mfma_f32_16x16x32_bf16 v[16:19], v[198:201], v[190:193], v[16:19]
	v_mfma_f32_16x16x32_bf16 v[8:11], v[236:239], v[190:193], v[8:11]
	v_mfma_f32_16x16x32_bf16 v[64:67], v[232:235], v[168:171], v[64:67]
	v_mfma_f32_16x16x32_bf16 v[56:59], v[240:243], v[168:171], v[56:59]
	v_mfma_f32_16x16x32_bf16 v[48:51], v[232:235], v[176:179], v[48:51]
	v_mfma_f32_16x16x32_bf16 v[40:43], v[240:243], v[176:179], v[40:43]
	v_mfma_f32_16x16x32_bf16 v[32:35], v[232:235], v[186:189], v[32:35]
	v_mfma_f32_16x16x32_bf16 v[24:27], v[240:243], v[186:189], v[24:27]
	v_mfma_f32_16x16x32_bf16 v[16:19], v[232:235], v[194:197], v[16:19]
	v_mfma_f32_16x16x32_bf16 v[8:11], v[240:243], v[194:197], v[8:11]
	s_add_u32 s24, s24, 0x100
	s_addc_u32 s25, s25, 0
	s_add_u32 s58, s58, 0x100
	s_addc_u32 s59, s59, 0
	s_cmp_ge_u32 s33, s1
	s_mov_b32 s29, s33
	s_barrier
	s_cbranch_scc0 .LBB0_1766
	s_branch .LBB0_1761
.LBB0_1767:
	s_setprio 0
	s_waitcnt vmcnt(0)
	s_cmpk_gt_u32 s3, 0xff
	s_cbranch_scc1 .LBB0_1769
	s_barrier

; template <class Epi>
; __device__ __forceinline__ void gemm_phase(LAS unsigned char* lds, const Gemm g, const StaticOrder& S, const Epi& E) {
;     ...
;     for (;;) {
;         const bool has_next = S.next(ui + 1, npm, npn, nk0, nnk, nsp);
;         const char* nA = has_next ? (const char*)g.A + (size_t)npm * tstep + (size_t)nk0 * kstep : cA; const char* nB = has_next ? (const char*)g.Bt + (size_t)npn * tstep + (size_t)nk0 * kstep : cB;
;         const int nt = cnk;
;         for (int t = 0; t < nt; t += 2) {
.LBB0_1847:
	s_cmpk_gt_u32 s28, 0xff
	s_cbranch_scc0 .Lmy_prio_p7
	s_setprio 1

; #define PG8_STAGE(bufoff, gbase, voff) do { _Pragma("unroll") for (int _i = 0; _i < 2; ++_i) \
;         __builtin_amdgcn_global_load_lds((const unsigned*)((const char*)(gbase) + (voff)[_i]), (LAS unsigned*)(lds + (bufoff) + ldsw + _i * 8192), 16, 0, 0); } while (0)
; #define PG8_LDA(dst, b, h) do { _Pragma("unroll") for (int m = 0; m < 4; ++m) _Pragma("unroll") for (int k = 0; k < 2; ++k) dst[m][k] = *(const LAS bf16x8*)(lds + PG8_SA(b, h) + aoff + m * 2048 + k * 1024); } while (0)
; #define PG8_LDB(dst, b, h) do { _Pragma("unroll") for (int n = 0; n < 2; ++n) _Pragma("unroll") for (int k = 0; k < 2; ++k) dst[n][k] = *(const LAS bf16x8*)(lds + PG8_SB(b, h) + boff + n * 2048 + k * 1024); } while (0)
; #define PG8_MMA(ai, bj, At, Bt) do { __builtin_amdgcn_s_setprio(1); _Pragma("unroll") for (int m = 0; m < 4; ++m) _Pragma("unroll") for (int n = 0; n < 2; ++n) _Pragma("unroll") for (int k = 0; k < 2; ++k) \
;         acc[ai][bj][m][n] = __builtin_amdgcn_mfma_f32_16x16x32_bf16(Bt[n][k], At[m][k], acc[ai][bj][m][n], 0, 0, 0); __builtin_amdgcn_s_setprio(0); } while (0)
; #define PG8_WAIT_L(n) asm volatile("s_waitcnt lgkmcnt(" #n ")" ::: "memory")
; #define PG8_BAR __builtin_amdgcn_s_barrier()
; #define PG8_SCHED __builtin_amdgcn_sched_barrier(0)
; template <class Epi>
; __device__ __forceinline__ void gemm_phase(LAS unsigned char* lds, const Gemm g, const StaticOrder& S, const Epi& E) {
;     ...
;             const bool last = (t == nt - 2);
;             const char* a1 = cA + (size_t)(t + 1) * kstep;
;             const char* a2 = last ? nA : cA + (size_t)(t + 2) * kstep; const char* b2 = last ? nB : cB + (size_t)(t + 2) * kstep;
;             const char* a3 = a2 + kstep; const char* b3 = b2 + kstep;
;             PG8_LDB(B0, 0, 0); PG8_SCHED; PG8_LDA(At, 0, 0); PG8_STAGE(PG8_SA(1, 1), a1 + hstep, voffA);
;             PG8_WAIT_L(8); PG8_BAR; PG8_WAIT_L(0); PG8_MMA(0, 0, At, B0); PG8_BAR; PG8_SCHED;
;             PG8_LDB(B1, 0, 1); PG8_STAGE(PG8_SB(0, 0), b2, voffB);
;             PG8_BAR; PG8_WAIT_L(0); PG8_MMA(0, 1, At, B1); PG8_BAR;
;             PG8_LDA(At, 0, 1); PG8_STAGE(PG8_SA(0, 0), a2, voffA);
;             PG8_BAR; PG8_WAIT_L(0); PG8_MMA(1, 0, At, B0); PG8_BAR; PG8_SCHED;
.LBB0_1859:
	s_add_i32 s87, s60, 2
	s_add_u32 s58, s56, 0x100
	s_addc_u32 s59, s57, 0
	s_add_i32 s8, 0, 0x10000
	v_add_u32_e32 v148, s8, v231
	ds_read_b128 v[136:139], v148
	ds_read_b128 v[140:143], v148 offset:1024
	ds_read_b128 v[144:147], v148 offset:2048
	ds_read_b128 v[148:151], v148 offset:3072
	s_cmp_eq_u32 s74, s60
	s_cselect_b32 s60, s54, s75
	s_cselect_b32 s63, s49, s59
	s_cselect_b32 s62, s48, s58
	s_cselect_b32 s61, s55, s78
	v_lshl_add_u64 v[190:191], s[56:57], 0, v[188:189]
	s_add_i32 m0, s33, 0xc000
	ds_read_b128 v[152:155], v233
	ds_read_b128 v[156:159], v233 offset:1024
	ds_read_b128 v[160:163], v233 offset:2048
	ds_read_b128 v[164:167], v233 offset:3072
	ds_read_b128 v[168:171], v233 offset:4096
	ds_read_b128 v[172:175], v233 offset:5120
	ds_read_b128 v[176:179], v233 offset:6144
	ds_read_b128 v[180:183], v233 offset:7168
	global_load_lds_dwordx4 v[190:191], off
	v_lshl_add_u64 v[190:191], s[56:57], 0, v[186:187]
	s_add_i32 m0, s33, 0xe000
	s_nop 0
	global_load_lds_dwordx4 v[190:191], off
	s_waitcnt lgkmcnt(8)
	s_barrier
	s_waitcnt lgkmcnt(0)
	s_waitcnt lgkmcnt(0)
	v_mfma_f32_16x16x32_bf16 v[132:135], v[136:139], v[152:155], v[132:135]
	v_mfma_f32_16x16x32_bf16 v[128:131], v[144:147], v[152:155], v[128:131]
	v_mfma_f32_16x16x32_bf16 v[116:119], v[136:139], v[160:163], v[116:119]
	v_mfma_f32_16x16x32_bf16 v[112:115], v[144:147], v[160:163], v[112:115]
	v_mfma_f32_16x16x32_bf16 v[100:103], v[136:139], v[168:171], v[100:103]
	v_mfma_f32_16x16x32_bf16 v[96:99], v[144:147], v[168:171], v[96:99]
	v_mfma_f32_16x16x32_bf16 v[84:87], v[136:139], v[176:179], v[84:87]
	v_mfma_f32_16x16x32_bf16 v[80:83], v[144:147], v[176:179], v[80:83]
	v_mfma_f32_16x16x32_bf16 v[132:135], v[140:143], v[156:159], v[132:135]
	v_mfma_f32_16x16x32_bf16 v[128:131], v[148:151], v[156:159], v[128:131]
	v_mfma_f32_16x16x32_bf16 v[116:119], v[140:143], v[164:167], v[116:119]
	v_mfma_f32_16x16x32_bf16 v[112:115], v[148:151], v[164:167], v[112:115]
	v_mfma_f32_16x16x32_bf16 v[100:103], v[140:143], v[172:175], v[100:103]
	v_mfma_f32_16x16x32_bf16 v[96:99], v[148:151], v[172:175], v[96:99]
	v_mfma_f32_16x16x32_bf16 v[84:87], v[140:143], v[180:183], v[84:87]
	v_mfma_f32_16x16x32_bf16 v[80:83], v[148:151], v[180:183], v[80:83]
	s_barrier
	s_add_i32 s89, 0, 0x14000
	v_add_u32_e32 v218, s89, v231
	s_add_i32 s8, s8, s3
	ds_read_b128 v[190:193], v218
	ds_read_b128 v[194:197], v218 offset:1024
	ds_read_b128 v[198:201], v218 offset:2048
	ds_read_b128 v[234:237], v218 offset:3072
	v_lshl_add_u64 v[218:219], s[60:61], 0, v[0:1]
	s_mov_b32 m0, s8
	v_lshl_add_u64 v[238:239], s[60:61], 0, v[2:3]
	global_load_lds_dwordx4 v[218:219], off
	s_add_i32 m0, s8, 0x2000
	s_nop 0
	global_load_lds_dwordx4 v[238:239], off
	s_barrier
	s_waitcnt lgkmcnt(0)
	s_waitcnt lgkmcnt(0)
	v_mfma_f32_16x16x32_bf16 v[124:127], v[190:193], v[152:155], v[124:127]
	v_mfma_f32_16x16x32_bf16 v[120:123], v[198:201], v[152:155], v[120:123]
	v_mfma_f32_16x16x32_bf16 v[108:111], v[190:193], v[160:163], v[108:111]
	v_mfma_f32_16x16x32_bf16 v[104:107], v[198:201], v[160:163], v[104:107]
	v_mfma_f32_16x16x32_bf16 v[92:95], v[190:193], v[168:171], v[92:95]
	v_mfma_f32_16x16x32_bf16 v[88:91], v[198:201], v[168:171], v[88:91]
	v_mfma_f32_16x16x32_bf16 v[76:79], v[190:193], v[176:179], v[76:79]
	v_mfma_f32_16x16x32_bf16 v[72:75], v[198:201], v[176:179], v[72:75]
	v_mfma_f32_16x16x32_bf16 v[124:127], v[194:197], v[156:159], v[124:127]
	v_mfma_f32_16x16x32_bf16 v[120:123], v[234:237], v[156:159], v[120:123]
	v_mfma_f32_16x16x32_bf16 v[108:111], v[194:197], v[164:167], v[108:111]
	v_mfma_f32_16x16x32_bf16 v[104:107], v[234:237], v[164:167], v[104:107]
	v_mfma_f32_16x16x32_bf16 v[92:95], v[194:197], v[172:175], v[92:95]
	v_mfma_f32_16x16x32_bf16 v[88:91], v[234:237], v[172:175], v[88:91]
	v_mfma_f32_16x16x32_bf16 v[76:79], v[194:197], v[180:183], v[76:79]
	v_mfma_f32_16x16x32_bf16 v[72:75], v[234:237], v[180:183], v[72:75]
	s_mov_b32 m0, s33
	v_lshl_add_u64 v[240:241], s[62:63], 0, v[0:1]
	s_barrier
	ds_read_b128 v[152:155], v233 offset:16384
	ds_read_b128 v[156:159], v233 offset:17408
	ds_read_b128 v[160:163], v233 offset:18432
	ds_read_b128 v[164:167], v233 offset:19456
	ds_read_b128 v[168:171], v233 offset:20480
	ds_read_b128 v[172:175], v233 offset:21504
	ds_read_b128 v[176:179], v233 offset:22528
	ds_read_b128 v[180:183], v233 offset:23552
	global_load_lds_dwordx4 v[240:241], off
	v_lshl_add_u64 v[242:243], s[62:63], 0, v[2:3]
	s_mov_b32 m0, s68
	s_nop 0
	global_load_lds_dwordx4 v[242:243], off
	s_barrier
	s_waitcnt lgkmcnt(0)
	s_waitcnt lgkmcnt(0)
	v_mfma_f32_16x16x32_bf16 v[68:71], v[136:139], v[152:155], v[68:71]
	v_mfma_f32_16x16x32_bf16 v[64:67], v[144:147], v[152:155], v[64:67]
	v_mfma_f32_16x16x32_bf16 v[52:55], v[136:139], v[160:163], v[52:55]
	v_mfma_f32_16x16x32_bf16 v[48:51], v[144:147], v[160:163], v[48:51]
	v_mfma_f32_16x16x32_bf16 v[36:39], v[136:139], v[168:171], v[36:39]
	v_mfma_f32_16x16x32_bf16 v[32:35], v[144:147], v[168:171], v[32:35]
	v_mfma_f32_16x16x32_bf16 v[20:23], v[136:139], v[176:179], v[20:23]
	v_mfma_f32_16x16x32_bf16 v[16:19], v[144:147], v[176:179], v[16:19]
	v_mfma_f32_16x16x32_bf16 v[68:71], v[140:143], v[156:159], v[68:71]
	v_mfma_f32_16x16x32_bf16 v[64:67], v[148:151], v[156:159], v[64:67]
	v_mfma_f32_16x16x32_bf16 v[52:55], v[140:143], v[164:167], v[52:55]
	v_mfma_f32_16x16x32_bf16 v[48:51], v[148:151], v[164:167], v[48:51]
	v_mfma_f32_16x16x32_bf16 v[36:39], v[140:143], v[172:175], v[36:39]
	v_mfma_f32_16x16x32_bf16 v[32:35], v[148:151], v[172:175], v[32:35]
	v_mfma_f32_16x16x32_bf16 v[20:23], v[140:143], v[180:183], v[20:23]
	v_mfma_f32_16x16x32_bf16 v[16:19], v[148:151], v[180:183], v[16:19]
	s_barrier
; #define PG8_STAGE(bufoff, gbase, voff) do { _Pragma("unroll") for (int _i = 0; _i < 2; ++_i) \
;         __builtin_amdgcn_global_load_lds((const unsigned*)((const char*)(gbase) + (voff)[_i]), (LAS unsigned*)(lds + (bufoff) + ldsw + _i * 8192), 16, 0, 0); } while (0)
; #define PG8_LDA(dst, b, h) do { _Pragma("unroll") for (int m = 0; m < 4; ++m) _Pragma("unroll") for (int k = 0; k < 2; ++k) dst[m][k] = *(const LAS bf16x8*)(lds + PG8_SA(b, h) + aoff + m * 2048 + k * 1024); } while (0)
; #define PG8_LDB(dst, b, h) do { _Pragma("unroll") for (int n = 0; n < 2; ++n) _Pragma("unroll") for (int k = 0; k < 2; ++k) dst[n][k] = *(const LAS bf16x8*)(lds + PG8_SB(b, h) + boff + n * 2048 + k * 1024); } while (0)
; #define PG8_MMA(ai, bj, At, Bt) do { __builtin_amdgcn_s_setprio(1); _Pragma("unroll") for (int m = 0; m < 4; ++m) _Pragma("unroll") for (int n = 0; n < 2; ++n) _Pragma("unroll") for (int k = 0; k < 2; ++k) \
;         acc[ai][bj][m][n] = __builtin_amdgcn_mfma_f32_16x16x32_bf16(Bt[n][k], At[m][k], acc[ai][bj][m][n], 0, 0, 0); __builtin_amdgcn_s_setprio(0); } while (0)
; #define PG8_WAIT_V(n) asm volatile("s_waitcnt vmcnt(" #n ")" ::: "memory")
; #define PG8_WAIT_L(n) asm volatile("s_waitcnt lgkmcnt(" #n ")" ::: "memory")
; #define PG8_BAR __builtin_amdgcn_s_barrier()
; #define PG8_SCHED __builtin_amdgcn_sched_barrier(0)
; template <class Epi>
; __device__ __forceinline__ void gemm_phase(LAS unsigned char* lds, const Gemm g, const StaticOrder& S, const Epi& E) {
;     ...
;             PG8_STAGE(PG8_SB(0, 1), b2 + hstep, voffB);
;             PG8_WAIT_V(6); PG8_BAR; PG8_MMA(1, 1, At, B1); PG8_BAR;
;             PG8_LDB(B0, 1, 0); PG8_SCHED; PG8_LDA(At, 1, 0); PG8_STAGE(PG8_SA(0, 1), a2 + hstep, voffA);
;             PG8_WAIT_L(8); PG8_BAR; PG8_WAIT_L(0); PG8_MMA(0, 0, At, B0); PG8_BAR; PG8_SCHED;
;             PG8_LDB(B1, 1, 1); PG8_STAGE(PG8_SB(1, 0), b3, voffB);
;             PG8_BAR; PG8_WAIT_L(0); PG8_MMA(0, 1, At, B1); PG8_BAR;
	s_add_u32 s56, s60, 0xb0000
	s_addc_u32 s57, s61, 0
	s_add_i32 s8, s89, s3
	v_lshl_add_u64 v[136:137], s[56:57], 0, v[0:1]
	s_mov_b32 m0, s8
	s_nop 0
	global_load_lds_dwordx4 v[136:137], off
	v_lshl_add_u64 v[136:137], s[56:57], 0, v[2:3]
	s_add_i32 m0, s8, 0x2000
	s_nop 0
	global_load_lds_dwordx4 v[136:137], off
	s_waitcnt vmcnt(6)
	s_barrier
	v_mfma_f32_16x16x32_bf16 v[60:63], v[190:193], v[152:155], v[60:63]
	v_mfma_f32_16x16x32_bf16 v[56:59], v[198:201], v[152:155], v[56:59]
	v_mfma_f32_16x16x32_bf16 v[44:47], v[190:193], v[160:163], v[44:47]
	v_mfma_f32_16x16x32_bf16 v[40:43], v[198:201], v[160:163], v[40:43]
	v_mfma_f32_16x16x32_bf16 v[28:31], v[190:193], v[168:171], v[28:31]
	v_mfma_f32_16x16x32_bf16 v[24:27], v[198:201], v[168:171], v[24:27]
	v_mfma_f32_16x16x32_bf16 v[12:15], v[190:193], v[176:179], v[12:15]
	v_mfma_f32_16x16x32_bf16 v[8:11], v[198:201], v[176:179], v[8:11]
	v_mfma_f32_16x16x32_bf16 v[60:63], v[194:197], v[156:159], v[60:63]
	v_mfma_f32_16x16x32_bf16 v[56:59], v[234:237], v[156:159], v[56:59]
	v_mfma_f32_16x16x32_bf16 v[44:47], v[194:197], v[164:167], v[44:47]
	v_mfma_f32_16x16x32_bf16 v[40:43], v[234:237], v[164:167], v[40:43]
	v_mfma_f32_16x16x32_bf16 v[28:31], v[194:197], v[172:175], v[28:31]
	v_mfma_f32_16x16x32_bf16 v[24:27], v[234:237], v[172:175], v[24:27]
	v_mfma_f32_16x16x32_bf16 v[12:15], v[194:197], v[180:183], v[12:15]
	v_mfma_f32_16x16x32_bf16 v[8:11], v[234:237], v[180:183], v[8:11]
	s_add_i32 s8, 0, 0x18000
	v_add_u32_e32 v148, s8, v231
	s_barrier
	ds_read_b128 v[136:139], v148
	ds_read_b128 v[140:143], v148 offset:1024
	ds_read_b128 v[144:147], v148 offset:2048
	ds_read_b128 v[148:151], v148 offset:3072
	s_add_u32 s56, s62, 0xb0000
	s_addc_u32 s57, s63, 0
	s_mov_b32 m0, s18
	v_lshl_add_u64 v[190:191], s[56:57], 0, v[0:1]
	ds_read_b128 v[152:155], v233 offset:32768
	ds_read_b128 v[156:159], v233 offset:33792
	ds_read_b128 v[160:163], v233 offset:34816
	ds_read_b128 v[164:167], v233 offset:35840
	ds_read_b128 v[168:171], v233 offset:36864
	ds_read_b128 v[172:175], v233 offset:37888
	ds_read_b128 v[176:179], v233 offset:38912
	ds_read_b128 v[180:183], v233 offset:39936
	global_load_lds_dwordx4 v[190:191], off
	v_lshl_add_u64 v[190:191], s[56:57], 0, v[2:3]
	s_mov_b32 m0, s19
	s_nop 0
	global_load_lds_dwordx4 v[190:191], off
	s_waitcnt lgkmcnt(8)
	s_barrier
	s_waitcnt lgkmcnt(0)
	s_waitcnt lgkmcnt(0)
	v_mfma_f32_16x16x32_bf16 v[132:135], v[136:139], v[152:155], v[132:135]
	v_mfma_f32_16x16x32_bf16 v[128:131], v[144:147], v[152:155], v[128:131]
	v_mfma_f32_16x16x32_bf16 v[116:119], v[136:139], v[160:163], v[116:119]
	v_mfma_f32_16x16x32_bf16 v[112:115], v[144:147], v[160:163], v[112:115]
	v_mfma_f32_16x16x32_bf16 v[100:103], v[136:139], v[168:171], v[100:103]
	v_mfma_f32_16x16x32_bf16 v[96:99], v[144:147], v[168:171], v[96:99]
	v_mfma_f32_16x16x32_bf16 v[84:87], v[136:139], v[176:179], v[84:87]
	v_mfma_f32_16x16x32_bf16 v[80:83], v[144:147], v[176:179], v[80:83]
	v_mfma_f32_16x16x32_bf16 v[132:135], v[140:143], v[156:159], v[132:135]
	v_mfma_f32_16x16x32_bf16 v[128:131], v[148:151], v[156:159], v[128:131]
	v_mfma_f32_16x16x32_bf16 v[116:119], v[140:143], v[164:167], v[116:119]
	v_mfma_f32_16x16x32_bf16 v[112:115], v[148:151], v[164:167], v[112:115]
	v_mfma_f32_16x16x32_bf16 v[100:103], v[140:143], v[172:175], v[100:103]
	v_mfma_f32_16x16x32_bf16 v[96:99], v[148:151], v[172:175], v[96:99]
	v_mfma_f32_16x16x32_bf16 v[84:87], v[140:143], v[180:183], v[84:87]
	v_mfma_f32_16x16x32_bf16 v[80:83], v[148:151], v[180:183], v[80:83]
	s_barrier
	s_add_i32 s62, 0, 0x1c000
	s_add_i32 s8, s8, s3
	v_add_u32_e32 v234, s62, v231
	v_lshl_add_u64 v[218:219], v[218:219], 0, s[12:13]
	s_mov_b32 m0, s8
	ds_read_b128 v[190:193], v234
	ds_read_b128 v[194:197], v234 offset:1024
	ds_read_b128 v[198:201], v234 offset:2048
	ds_read_b128 v[234:237], v234 offset:3072
	global_load_lds_dwordx4 v[218:219], off
	v_lshl_add_u64 v[218:219], v[238:239], 0, s[12:13]
	s_add_i32 m0, s8, 0x2000
	s_nop 0
	global_load_lds_dwordx4 v[218:219], off
	s_barrier
; #define PG8_STAGE(bufoff, gbase, voff) do { _Pragma("unroll") for (int _i = 0; _i < 2; ++_i) \
;         __builtin_amdgcn_global_load_lds((const unsigned*)((const char*)(gbase) + (voff)[_i]), (LAS unsigned*)(lds + (bufoff) + ldsw + _i * 8192), 16, 0, 0); } while (0)
; #define PG8_LDA(dst, b, h) do { _Pragma("unroll") for (int m = 0; m < 4; ++m) _Pragma("unroll") for (int k = 0; k < 2; ++k) dst[m][k] = *(const LAS bf16x8*)(lds + PG8_SA(b, h) + aoff + m * 2048 + k * 1024); } while (0)
; #define PG8_MMA(ai, bj, At, Bt) do { __builtin_amdgcn_s_setprio(1); _Pragma("unroll") for (int m = 0; m < 4; ++m) _Pragma("unroll") for (int n = 0; n < 2; ++n) _Pragma("unroll") for (int k = 0; k < 2; ++k) \
;         acc[ai][bj][m][n] = __builtin_amdgcn_mfma_f32_16x16x32_bf16(Bt[n][k], At[m][k], acc[ai][bj][m][n], 0, 0, 0); __builtin_amdgcn_s_setprio(0); } while (0)
; #define PG8_WAIT_V(n) asm volatile("s_waitcnt vmcnt(" #n ")" ::: "memory")
; #define PG8_WAIT_L(n) asm volatile("s_waitcnt lgkmcnt(" #n ")" ::: "memory")
; #define PG8_BAR __builtin_amdgcn_s_barrier()
; #define PG8_SCHED __builtin_amdgcn_sched_barrier(0)
; template <class Epi>
; __device__ __forceinline__ void gemm_phase(LAS unsigned char* lds, const Gemm g, const StaticOrder& S, const Epi& E) {
;     ...
;             PG8_BAR; PG8_WAIT_L(0); PG8_MMA(0, 1, At, B1); PG8_BAR;
;             PG8_LDA(At, 1, 1); PG8_STAGE(PG8_SA(1, 0), a3, voffA);
;             PG8_BAR; PG8_WAIT_L(0); PG8_MMA(1, 0, At, B0); PG8_BAR; PG8_SCHED;
;             PG8_STAGE(PG8_SB(1, 1), b3 + hstep, voffB);
;             PG8_WAIT_V(6); PG8_BAR; PG8_MMA(1, 1, At, B1); PG8_BAR;
	s_waitcnt lgkmcnt(0)
	s_waitcnt lgkmcnt(0)
	v_mfma_f32_16x16x32_bf16 v[124:127], v[190:193], v[152:155], v[124:127]
	v_mfma_f32_16x16x32_bf16 v[120:123], v[198:201], v[152:155], v[120:123]
	v_mfma_f32_16x16x32_bf16 v[108:111], v[190:193], v[160:163], v[108:111]
	v_mfma_f32_16x16x32_bf16 v[104:107], v[198:201], v[160:163], v[104:107]
	v_mfma_f32_16x16x32_bf16 v[92:95], v[190:193], v[168:171], v[92:95]
	v_mfma_f32_16x16x32_bf16 v[88:91], v[198:201], v[168:171], v[88:91]
	v_mfma_f32_16x16x32_bf16 v[76:79], v[190:193], v[176:179], v[76:79]
	v_mfma_f32_16x16x32_bf16 v[72:75], v[198:201], v[176:179], v[72:75]
	v_mfma_f32_16x16x32_bf16 v[124:127], v[194:197], v[156:159], v[124:127]
	v_mfma_f32_16x16x32_bf16 v[120:123], v[234:237], v[156:159], v[120:123]
	v_mfma_f32_16x16x32_bf16 v[108:111], v[194:197], v[164:167], v[108:111]
	v_mfma_f32_16x16x32_bf16 v[104:107], v[234:237], v[164:167], v[104:107]
	v_mfma_f32_16x16x32_bf16 v[92:95], v[194:197], v[172:175], v[92:95]
	v_mfma_f32_16x16x32_bf16 v[88:91], v[234:237], v[172:175], v[88:91]
	v_mfma_f32_16x16x32_bf16 v[76:79], v[194:197], v[180:183], v[76:79]
	v_mfma_f32_16x16x32_bf16 v[72:75], v[234:237], v[180:183], v[72:75]
	s_mov_b32 m0, s23
	v_lshl_add_u64 v[218:219], v[240:241], 0, s[12:13]
	s_barrier
	ds_read_b128 v[152:155], v233 offset:49152
	ds_read_b128 v[156:159], v233 offset:50176
	ds_read_b128 v[160:163], v233 offset:51200
	ds_read_b128 v[164:167], v233 offset:52224
	ds_read_b128 v[168:171], v233 offset:53248
	ds_read_b128 v[172:175], v233 offset:54272
	ds_read_b128 v[176:179], v233 offset:55296
	ds_read_b128 v[180:183], v233 offset:56320
	global_load_lds_dwordx4 v[218:219], off
	v_lshl_add_u64 v[218:219], v[242:243], 0, s[12:13]
	s_mov_b32 m0, s70
	s_nop 0
	global_load_lds_dwordx4 v[218:219], off
	s_barrier
	s_waitcnt lgkmcnt(0)
	s_waitcnt lgkmcnt(0)
	v_mfma_f32_16x16x32_bf16 v[68:71], v[136:139], v[152:155], v[68:71]
	v_mfma_f32_16x16x32_bf16 v[64:67], v[144:147], v[152:155], v[64:67]
	v_mfma_f32_16x16x32_bf16 v[52:55], v[136:139], v[160:163], v[52:55]
	v_mfma_f32_16x16x32_bf16 v[48:51], v[144:147], v[160:163], v[48:51]
	v_mfma_f32_16x16x32_bf16 v[36:39], v[136:139], v[168:171], v[36:39]
	v_mfma_f32_16x16x32_bf16 v[32:35], v[144:147], v[168:171], v[32:35]
	v_mfma_f32_16x16x32_bf16 v[20:23], v[136:139], v[176:179], v[20:23]
	v_mfma_f32_16x16x32_bf16 v[16:19], v[144:147], v[176:179], v[16:19]
	v_mfma_f32_16x16x32_bf16 v[68:71], v[140:143], v[156:159], v[68:71]
	v_mfma_f32_16x16x32_bf16 v[64:67], v[148:151], v[156:159], v[64:67]
	v_mfma_f32_16x16x32_bf16 v[52:55], v[140:143], v[164:167], v[52:55]
	v_mfma_f32_16x16x32_bf16 v[48:51], v[148:151], v[164:167], v[48:51]
	v_mfma_f32_16x16x32_bf16 v[36:39], v[140:143], v[172:175], v[36:39]
	v_mfma_f32_16x16x32_bf16 v[32:35], v[148:151], v[172:175], v[32:35]
	v_mfma_f32_16x16x32_bf16 v[20:23], v[140:143], v[180:183], v[20:23]
	v_mfma_f32_16x16x32_bf16 v[16:19], v[148:151], v[180:183], v[16:19]
	s_barrier
	s_add_u32 s56, s60, 0xb0080
	s_addc_u32 s57, s61, 0
	s_add_i32 s8, s62, s3
	v_lshl_add_u64 v[136:137], s[56:57], 0, v[0:1]
	s_mov_b32 m0, s8
	s_nop 0
	global_load_lds_dwordx4 v[136:137], off
	v_lshl_add_u64 v[136:137], s[56:57], 0, v[2:3]
	s_add_i32 m0, s8, 0x2000
	s_nop 0
	global_load_lds_dwordx4 v[136:137], off
	s_waitcnt vmcnt(6)
	s_barrier
	v_mfma_f32_16x16x32_bf16 v[60:63], v[190:193], v[152:155], v[60:63]
	v_mfma_f32_16x16x32_bf16 v[56:59], v[198:201], v[152:155], v[56:59]
	v_mfma_f32_16x16x32_bf16 v[44:47], v[190:193], v[160:163], v[44:47]
	v_mfma_f32_16x16x32_bf16 v[40:43], v[198:201], v[160:163], v[40:43]
	v_mfma_f32_16x16x32_bf16 v[28:31], v[190:193], v[168:171], v[28:31]
	v_mfma_f32_16x16x32_bf16 v[24:27], v[198:201], v[168:171], v[24:27]
	v_mfma_f32_16x16x32_bf16 v[12:15], v[190:193], v[176:179], v[12:15]
	v_mfma_f32_16x16x32_bf16 v[8:11], v[198:201], v[176:179], v[8:11]
	v_mfma_f32_16x16x32_bf16 v[60:63], v[194:197], v[156:159], v[60:63]
	v_mfma_f32_16x16x32_bf16 v[56:59], v[234:237], v[156:159], v[56:59]
	v_mfma_f32_16x16x32_bf16 v[44:47], v[194:197], v[164:167], v[44:47]
	v_mfma_f32_16x16x32_bf16 v[40:43], v[234:237], v[164:167], v[40:43]
	v_mfma_f32_16x16x32_bf16 v[28:31], v[194:197], v[172:175], v[28:31]
	v_mfma_f32_16x16x32_bf16 v[24:27], v[234:237], v[172:175], v[24:27]
	v_mfma_f32_16x16x32_bf16 v[12:15], v[194:197], v[180:183], v[12:15]
	v_mfma_f32_16x16x32_bf16 v[8:11], v[234:237], v[180:183], v[8:11]
	s_add_u32 s75, s75, 0x100
	s_addc_u32 s78, s78, 0
	s_cmp_ge_i32 s87, s73
	s_mov_b64 s[56:57], s[58:59]
	s_mov_b32 s60, s87
	s_barrier
	s_cbranch_scc0 .LBB0_1859
	v_readlane_b32 s78, v255, 24
	s_mov_b32 s87, 0x8000

; #define PG8_WAIT_V(n) asm volatile("s_waitcnt vmcnt(" #n ")" ::: "memory")
; #define PG8_BAR __builtin_amdgcn_s_barrier()
; template <class Epi>
; __device__ __forceinline__ void gemm_phase(LAS unsigned char* lds, const Gemm g, const StaticOrder& S, const Epi& E) {
;     ...
;     PG8_WAIT_V(0);
;     if (wr == 0) PG8_BAR;
.LBB0_1930:
	s_setprio 0
	s_waitcnt vmcnt(0)
	s_cmpk_gt_u32 s28, 0xff
	s_cbranch_scc1 .LBB0_1932
	s_barrier
